# sample-row small GEMM k-loops: all operand loads issued up front behind counted waits (4 copies, K=1024 and K=2816 paths)
# baseline (speedup 1.0000x reference)
; template <int MODE>
; __device__ __forceinline__ void small_gemm(const bf16_t* A, const bf16_t* Bt, int Npos, int K, const LAS unsigned long long* eap, LAS unsigned char* lds, int wg, int G, int wid, int lane) {
;     ...
;         const bf16_t* ap = A + (size_t)(r0 + fr) * K + wid * KW + 8 * fq;
;         const bf16_t* bp = Bt + (size_t)(p0 + fr) * K + wid * KW + 8 * fq;
;         for (int k0 = 0; k0 < KW; k0 += 32) {
;             const bf16x8 av = *(const bf16x8*)(ap + k0);
;             bf16x8 wv[4];
; #pragma unroll
;             for (int f = 0; f < 4; ++f) wv[f] = *(const bf16x8*)(bp + (size_t)(16 * f) * K + k0);
; #pragma unroll
;             for (int f = 0; f < 4; ++f) acc[f] = __builtin_amdgcn_mfma_f32_16x16x32_bf16(wv[f], av, acc[f], 0, 0, 0);
;         }
; #pragma unroll
;         for (int f = 0; f < 4; ++f) part[(wid * 4 + f) * 64 + lane] = acc[f];
;         __syncthreads();
.LBB0_294:
	s_ashr_i32 s13, s12, 31
	s_lshr_b32 s13, s13, 29
	s_add_i32 s14, s12, s13
	s_ashr_i32 s13, s14, 3
	s_and_b32 s14, s14, 0xffffff8
	v_lshl_or_b32 v0, s13, 6, v165
	s_sub_i32 s14, s12, s14
	v_lshlrev_b32_e32 v2, 1, v0
	v_lshl_add_u32 v160, s14, 4, v167
	v_or_b32_e32 v3, 32, v2
	v_or_b32_e32 v2, 64, v2
	v_ashrrev_i32_e32 v1, 31, v0
	v_mad_u64_u32 v[16:17], s[14:15], s4, v160, v[18:19]
	v_mad_i64_i32 v[26:27], s[14:15], s4, v0, v[20:21]
	v_mad_u64_u32 v[28:29], s[14:15], s48, v3, v[20:21]
	v_mad_u64_u32 v[30:31], s[14:15], s48, v2, v[20:21]
	v_mad_i64_i32 v[32:33], s[14:15], s4, v0, v[22:23]
	v_mov_b32_e32 v0, 0
	v_mad_i32_i24 v29, s48, v1, v29
	v_mad_i32_i24 v31, s48, v1, v31
	s_mov_b32 s14, 0
	v_mov_b32_e32 v1, v0
	v_mov_b32_e32 v2, v0
	v_mov_b32_e32 v3, v0
	v_mov_b32_e32 v4, v0
	v_mov_b32_e32 v5, v0
	v_mov_b32_e32 v6, v0
	v_mov_b32_e32 v7, v0
	v_mov_b32_e32 v8, v0
	v_mov_b32_e32 v9, v0
	v_mov_b32_e32 v10, v0
	v_mov_b32_e32 v11, v0
	v_mov_b32_e32 v12, v0
	v_mov_b32_e32 v13, v0
	v_mov_b32_e32 v14, v0
	v_mov_b32_e32 v15, v0
	v_lshl_add_u64 v[52:53], v[16:17], 0, s[18:19]
	global_load_dwordx4 v[52:55], v[52:53], off offset:0
	v_lshl_add_u64 v[56:57], v[26:27], 0, s[18:19]
	global_load_dwordx4 v[56:59], v[56:57], off offset:0
	v_lshl_add_u64 v[60:61], v[28:29], 0, s[18:19]
	global_load_dwordx4 v[60:63], v[60:61], off offset:0
	v_lshl_add_u64 v[64:65], v[30:31], 0, s[18:19]
	global_load_dwordx4 v[64:67], v[64:65], off offset:0
	v_lshl_add_u64 v[68:69], v[32:33], 0, s[18:19]
	global_load_dwordx4 v[68:71], v[68:69], off offset:0
	v_lshl_add_u64 v[72:73], v[16:17], 0, s[18:19]
	global_load_dwordx4 v[72:75], v[72:73], off offset:64
	v_lshl_add_u64 v[76:77], v[26:27], 0, s[18:19]
	global_load_dwordx4 v[76:79], v[76:77], off offset:64
	v_lshl_add_u64 v[80:81], v[28:29], 0, s[18:19]
	global_load_dwordx4 v[80:83], v[80:81], off offset:64
	v_lshl_add_u64 v[84:85], v[30:31], 0, s[18:19]
	global_load_dwordx4 v[84:87], v[84:85], off offset:64
	v_lshl_add_u64 v[88:89], v[32:33], 0, s[18:19]
	global_load_dwordx4 v[88:91], v[88:89], off offset:64
	v_lshl_add_u64 v[92:93], v[16:17], 0, s[18:19]
	global_load_dwordx4 v[92:95], v[92:93], off offset:128
	v_lshl_add_u64 v[96:97], v[26:27], 0, s[18:19]
	global_load_dwordx4 v[96:99], v[96:97], off offset:128
	v_lshl_add_u64 v[100:101], v[28:29], 0, s[18:19]
	global_load_dwordx4 v[100:103], v[100:101], off offset:128
	v_lshl_add_u64 v[104:105], v[30:31], 0, s[18:19]
	global_load_dwordx4 v[104:107], v[104:105], off offset:128
	v_lshl_add_u64 v[108:109], v[32:33], 0, s[18:19]
	global_load_dwordx4 v[108:111], v[108:109], off offset:128
	v_lshl_add_u64 v[112:113], v[16:17], 0, s[18:19]
	global_load_dwordx4 v[112:115], v[112:113], off offset:192
	v_lshl_add_u64 v[116:117], v[26:27], 0, s[18:19]
	global_load_dwordx4 v[116:119], v[116:117], off offset:192
	v_lshl_add_u64 v[120:121], v[28:29], 0, s[18:19]
	global_load_dwordx4 v[120:123], v[120:121], off offset:192
	v_lshl_add_u64 v[124:125], v[30:31], 0, s[18:19]
	global_load_dwordx4 v[124:127], v[124:125], off offset:192
	v_lshl_add_u64 v[128:129], v[32:33], 0, s[18:19]
	global_load_dwordx4 v[128:131], v[128:129], off offset:192
	s_waitcnt vmcnt(18)
	v_mfma_f32_16x16x32_bf16 v[4:7], v[56:59], v[52:55], v[4:7]
	s_waitcnt vmcnt(17)
	v_mfma_f32_16x16x32_bf16 v[8:11], v[60:63], v[52:55], v[8:11]
	s_waitcnt vmcnt(16)
	v_mfma_f32_16x16x32_bf16 v[12:15], v[64:67], v[52:55], v[12:15]
	s_waitcnt vmcnt(15)
	v_mfma_f32_16x16x32_bf16 v[0:3], v[68:71], v[52:55], v[0:3]
	s_waitcnt vmcnt(13)
	v_mfma_f32_16x16x32_bf16 v[4:7], v[76:79], v[72:75], v[4:7]
	s_waitcnt vmcnt(12)
	v_mfma_f32_16x16x32_bf16 v[8:11], v[80:83], v[72:75], v[8:11]
	s_waitcnt vmcnt(11)
	v_mfma_f32_16x16x32_bf16 v[12:15], v[84:87], v[72:75], v[12:15]
	s_waitcnt vmcnt(10)
	v_mfma_f32_16x16x32_bf16 v[0:3], v[88:91], v[72:75], v[0:3]
	s_waitcnt vmcnt(8)
	v_mfma_f32_16x16x32_bf16 v[4:7], v[96:99], v[92:95], v[4:7]
	s_waitcnt vmcnt(7)
	v_mfma_f32_16x16x32_bf16 v[8:11], v[100:103], v[92:95], v[8:11]
	s_waitcnt vmcnt(6)
	v_mfma_f32_16x16x32_bf16 v[12:15], v[104:107], v[92:95], v[12:15]
	s_waitcnt vmcnt(5)
	v_mfma_f32_16x16x32_bf16 v[0:3], v[108:111], v[92:95], v[0:3]
	s_waitcnt vmcnt(3)
	v_mfma_f32_16x16x32_bf16 v[4:7], v[116:119], v[112:115], v[4:7]
	s_waitcnt vmcnt(2)
	v_mfma_f32_16x16x32_bf16 v[8:11], v[120:123], v[112:115], v[8:11]
	s_waitcnt vmcnt(1)
	v_mfma_f32_16x16x32_bf16 v[12:15], v[124:127], v[112:115], v[12:15]
	s_waitcnt vmcnt(0)
	v_mfma_f32_16x16x32_bf16 v[0:3], v[128:131], v[112:115], v[0:3]
	v_add_u32_e32 v16, s2, v42
	s_and_b64 vcc, exec, s[0:1]
	ds_write_b128 v16, v[4:7]
	ds_write_b128 v16, v[8:11] offset:1024
	s_nop 0
	ds_write_b128 v16, v[12:15] offset:2048
	s_nop 0
	ds_write_b128 v16, v[0:3] offset:3072
	s_waitcnt lgkmcnt(0)
	s_barrier
	s_cbranch_vccz .LBB0_293
; template <int MODE>
; __device__ __forceinline__ void small_gemm(const bf16_t* A, const bf16_t* Bt, int Npos, int K, const LAS unsigned long long* eap, LAS unsigned char* lds, int wg, int G, int wid, int lane) {
;     ...
;         if (wid == 0) {
; #pragma unroll
;             for (int w = 1; w < 8; ++w)
; #pragma unroll
;                 for (int f = 0; f < 4; ++f) acc[f] += part[(w * 4 + f) * 64 + lane];
;             const int row = r0 + fr;
;             const EpiArgs a = load_ea(eap);
	ds_read_b128 v[26:29], v42 offset:4096
	v_readlane_b32 s14, v245, 2
	s_lshl_b32 s28, s13, 5
	v_mov_b32_e32 v25, v161
	s_ashr_i32 s29, s28, 31
	s_waitcnt lgkmcnt(0)
	v_pk_add_f32 v[16:17], v[6:7], v[28:29]
	v_pk_add_f32 v[26:27], v[4:5], v[26:27]
	ds_read_b128 v[4:7], v42 offset:5120
	s_waitcnt lgkmcnt(0)
	v_pk_add_f32 v[10:11], v[10:11], v[6:7]
	v_pk_add_f32 v[8:9], v[8:9], v[4:5]
	ds_read_b128 v[4:7], v42 offset:6144
	s_waitcnt lgkmcnt(0)
	v_pk_add_f32 v[14:15], v[14:15], v[6:7]
	v_pk_add_f32 v[12:13], v[12:13], v[4:5]
	ds_read_b128 v[4:7], v42 offset:7168
	s_waitcnt lgkmcnt(0)
	v_pk_add_f32 v[6:7], v[2:3], v[6:7]
	v_pk_add_f32 v[4:5], v[0:1], v[4:5]
	ds_read_b128 v[0:3], v42 offset:8192
	s_waitcnt lgkmcnt(0)
	v_pk_add_f32 v[16:17], v[16:17], v[2:3]
	v_pk_add_f32 v[26:27], v[26:27], v[0:1]
	ds_read_b128 v[0:3], v42 offset:9216
	s_waitcnt lgkmcnt(0)
	v_pk_add_f32 v[10:11], v[10:11], v[2:3]
	v_pk_add_f32 v[8:9], v[8:9], v[0:1]
	ds_read_b128 v[0:3], v42 offset:10240
	s_waitcnt lgkmcnt(0)
	v_pk_add_f32 v[14:15], v[14:15], v[2:3]
	v_pk_add_f32 v[12:13], v[12:13], v[0:1]
	ds_read_b128 v[0:3], v42 offset:11264
	s_waitcnt lgkmcnt(0)
	v_pk_add_f32 v[6:7], v[6:7], v[2:3]
	v_pk_add_f32 v[4:5], v[4:5], v[0:1]
	ds_read_b128 v[0:3], v42 offset:12288
	s_waitcnt lgkmcnt(0)
	v_pk_add_f32 v[16:17], v[16:17], v[2:3]
	v_pk_add_f32 v[26:27], v[26:27], v[0:1]
	ds_read_b128 v[0:3], v42 offset:13312
	s_waitcnt lgkmcnt(0)
	v_pk_add_f32 v[10:11], v[10:11], v[2:3]
	v_pk_add_f32 v[8:9], v[8:9], v[0:1]
	ds_read_b128 v[0:3], v42 offset:14336
	s_waitcnt lgkmcnt(0)
	v_pk_add_f32 v[14:15], v[14:15], v[2:3]
	v_pk_add_f32 v[12:13], v[12:13], v[0:1]
	ds_read_b128 v[0:3], v42 offset:15360
	s_waitcnt lgkmcnt(0)
	v_pk_add_f32 v[6:7], v[6:7], v[2:3]
	v_pk_add_f32 v[4:5], v[4:5], v[0:1]
	ds_read_b128 v[0:3], v42 offset:16384
	s_waitcnt lgkmcnt(0)
	v_pk_add_f32 v[16:17], v[16:17], v[2:3]
	v_pk_add_f32 v[26:27], v[26:27], v[0:1]
	ds_read_b128 v[0:3], v42 offset:17408
	s_waitcnt lgkmcnt(0)
	v_pk_add_f32 v[10:11], v[10:11], v[2:3]
	v_pk_add_f32 v[8:9], v[8:9], v[0:1]
	ds_read_b128 v[0:3], v42 offset:18432
	s_waitcnt lgkmcnt(0)
	v_pk_add_f32 v[14:15], v[14:15], v[2:3]
	v_pk_add_f32 v[12:13], v[12:13], v[0:1]
	ds_read_b128 v[0:3], v42 offset:19456
	s_waitcnt lgkmcnt(0)
	v_pk_add_f32 v[6:7], v[6:7], v[2:3]
	v_pk_add_f32 v[4:5], v[4:5], v[0:1]
	ds_read_b128 v[0:3], v42 offset:20480
	s_waitcnt lgkmcnt(0)
	v_pk_add_f32 v[16:17], v[16:17], v[2:3]
	v_pk_add_f32 v[26:27], v[26:27], v[0:1]
	ds_read_b128 v[0:3], v42 offset:21504
	s_waitcnt lgkmcnt(0)
	v_pk_add_f32 v[10:11], v[10:11], v[2:3]
	v_pk_add_f32 v[8:9], v[8:9], v[0:1]
	ds_read_b128 v[0:3], v42 offset:22528
	s_waitcnt lgkmcnt(0)
	v_pk_add_f32 v[14:15], v[14:15], v[2:3]
	v_pk_add_f32 v[12:13], v[12:13], v[0:1]
	ds_read_b128 v[0:3], v42 offset:23552
	s_waitcnt lgkmcnt(0)
	v_pk_add_f32 v[6:7], v[6:7], v[2:3]
	v_pk_add_f32 v[4:5], v[4:5], v[0:1]
	ds_read_b128 v[0:3], v42 offset:24576
	s_waitcnt lgkmcnt(0)
	v_pk_add_f32 v[16:17], v[16:17], v[2:3]
	v_pk_add_f32 v[26:27], v[26:27], v[0:1]
	ds_read_b128 v[0:3], v42 offset:25600
	s_waitcnt lgkmcnt(0)
	v_pk_add_f32 v[10:11], v[10:11], v[2:3]
	v_pk_add_f32 v[8:9], v[8:9], v[0:1]
	ds_read_b128 v[0:3], v42 offset:26624
	s_waitcnt lgkmcnt(0)
	v_pk_add_f32 v[14:15], v[14:15], v[2:3]
	v_pk_add_f32 v[12:13], v[12:13], v[0:1]
	ds_read_b128 v[0:3], v42 offset:27648
	s_waitcnt lgkmcnt(0)
	v_pk_add_f32 v[6:7], v[6:7], v[2:3]
	v_pk_add_f32 v[4:5], v[4:5], v[0:1]
	ds_read_b128 v[0:3], v42 offset:28672
	s_waitcnt lgkmcnt(0)
	v_pk_add_f32 v[34:35], v[16:17], v[2:3]
	v_pk_add_f32 v[36:37], v[26:27], v[0:1]
	ds_read_b128 v[0:3], v42 offset:29696
	s_waitcnt lgkmcnt(0)
; #define GAS __attribute__((address_space(1)))
; __device__ __forceinline__ unsigned pk2(float lo, float hi) { const f32x2 v = {lo, hi}; return __builtin_bit_cast(unsigned, __builtin_convertvector(v, hwbf16x2)); }
; __device__ __forceinline__ float silu_f(float x) { return x * fast_rcp(1.0f + __expf(-x)); }
; template <int MODE, bool SMALL>
; __device__ __forceinline__ float epi_apply(const EpiArgs& a, int row, int g32, int fq, f32x4 v0, f32x4 v1, float rstd) {
;     ...
;     } else {
;         v0 *= rstd; v1 *= rstd;
;         float h[4];
; #pragma unroll
;         for (int j = 0; j < 4; ++j) h[j] = silu_f(v0[j]) * v1[j];
;         u32x2 w; w.x = pk2(h[0], h[1]); w.y = pk2(h[2], h[3]);
;         *(GAS u32x2*)(a.out + (size_t)row * DFF + 16 * g32 + 4 * fq) = w;
;         return 0.f;
; template <int MODE>
; __device__ __forceinline__ void small_gemm(const bf16_t* A, const bf16_t* Bt, int Npos, int K, const LAS unsigned long long* eap, LAS unsigned char* lds, int wg, int G, int wid, int lane) {
;     ...
;             const int row = r0 + fr;
;             const EpiArgs a = load_ea(eap);
;             float rstd = 1.f; if constexpr (MODE != 2) rstd = row_rstd(a.ssp, row);
;             float ss = 0.f;
; #pragma unroll
;             for (int gq = 0; gq < 2; ++gq) ss += epi_apply<MODE, true>(a, row, (p0 >> 5) + gq, fq, acc[2 * gq], acc[2 * gq + 1], rstd);
	v_pk_add_f32 v[38:39], v[10:11], v[2:3]
	v_pk_add_f32 v[40:41], v[8:9], v[0:1]
	ds_read_b128 v[0:3], v42 offset:30720
	s_waitcnt lgkmcnt(0)
	v_pk_add_f32 v[26:27], v[14:15], v[2:3]
	v_pk_add_f32 v[28:29], v[12:13], v[0:1]
	ds_read_b128 v[0:3], v42 offset:31744
	s_waitcnt lgkmcnt(0)
	v_pk_add_f32 v[32:33], v[4:5], v[0:1]
	v_mov_b32_e32 v0, s14
	v_pk_add_f32 v[30:31], v[6:7], v[2:3]
	ds_read_b128 v[0:3], v0
	v_lshlrev_b64 v[4:5], 6, v[160:161]
	s_movk_i32 s14, 0xb00
	v_mul_lo_u32 v160, v160, s14
	s_waitcnt lgkmcnt(0)
	v_lshl_add_u64 v[14:15], v[2:3], 0, v[4:5]
	global_load_dwordx4 v[2:5], v[14:15], off offset:48
	global_load_dwordx4 v[6:9], v[14:15], off offset:32
	global_load_dwordx4 v[10:13], v[14:15], off offset:16
	s_nop 0
	global_load_dwordx4 v[14:17], v[14:15], off
	v_lshl_add_u64 v[0:1], v[160:161], 1, v[0:1]
	v_lshl_add_u64 v[0:1], v[0:1], 0, v[24:25]
	v_lshl_add_u64 v[0:1], s[28:29], 1, v[0:1]
	s_waitcnt vmcnt(2)
	v_add_f32_e32 v6, v6, v7
	v_add_f32_e32 v8, v8, v9
	s_waitcnt vmcnt(0)
	v_mov_b32_e32 v44, v15
	v_mov_b32_e32 v45, v16
	v_mov_b32_e32 v15, v17
	v_mov_b32_e32 v16, v11
	v_mov_b32_e32 v17, v12
	v_mov_b32_e32 v11, v13
	v_pk_add_f32 v[14:15], v[44:45], v[14:15]
	v_pk_add_f32 v[10:11], v[16:17], v[10:11]
	v_pk_add_f32 v[14:15], v[14:15], v[14:15] op_sel:[0,1] op_sel_hi:[1,0]
	v_pk_add_f32 v[10:11], v[10:11], v[10:11] op_sel:[0,1] op_sel_hi:[1,0]
	v_mov_b32_e32 v15, v2
	v_mov_b32_e32 v11, v3
	v_mov_b32_e32 v7, v4
	v_mov_b32_e32 v9, v5
	v_pk_add_f32 v[2:3], v[14:15], v[10:11]
	v_pk_add_f32 v[4:5], v[6:7], v[8:9]
	s_nop 0
	v_pk_add_f32 v[2:3], v[2:3], v[4:5]
	s_nop 0
	v_add_f32_e32 v2, v2, v3
	v_fmamk_f32 v2, v2, 0x3a800000, v162
	v_cmp_gt_f32_e32 vcc, s3, v2
	v_mul_f32_e32 v3, 0x4b800000, v2
	s_nop 0
	v_cndmask_b32_e32 v2, v2, v3, vcc
	v_rsq_f32_e32 v2, v2
	s_nop 0
	v_mul_f32_e32 v3, 0x45800000, v2
	v_cndmask_b32_e32 v2, v2, v3, vcc
	v_pk_mul_f32 v[6:7], v[36:37], v[2:3] op_sel_hi:[1,0]
	v_pk_mul_f32 v[4:5], v[34:35], v[2:3] op_sel_hi:[1,0]
	v_pk_mul_f32 v[8:9], v[38:39], v[2:3] op_sel_hi:[1,0]
	v_pk_mul_f32 v[10:11], v[40:41], v[2:3] op_sel_hi:[1,0]
	v_mul_f32_e32 v3, 0xbfb8aa3b, v6
	v_exp_f32_e32 v3, v3
	s_nop 0
	v_add_f32_e32 v3, 1.0, v3
	v_rcp_f32_e32 v12, v3
	v_mul_f32_e32 v3, 0xbfb8aa3b, v7
	v_exp_f32_e32 v3, v3
	s_nop 0
	v_add_f32_e32 v3, 1.0, v3
	v_rcp_f32_e32 v13, v3
	v_mul_f32_e32 v3, 0xbfb8aa3b, v4
	v_exp_f32_e32 v3, v3
	v_pk_mul_f32 v[6:7], v[6:7], v[12:13]
	s_nop 0
	v_pk_mul_f32 v[6:7], v[10:11], v[6:7]
	v_add_f32_e32 v3, 1.0, v3
	v_rcp_f32_e32 v10, v3
	v_mul_f32_e32 v3, 0xbfb8aa3b, v5
	v_exp_f32_e32 v3, v3
	v_cvt_pk_bf16_f32 v6, v6, v7
	v_add_f32_e32 v3, 1.0, v3
	v_rcp_f32_e32 v11, v3
	s_nop 0
	v_pk_mul_f32 v[4:5], v[4:5], v[10:11]
	s_nop 0
	v_pk_mul_f32 v[4:5], v[8:9], v[4:5]
	v_pk_mul_f32 v[8:9], v[30:31], v[2:3] op_sel_hi:[1,0]
	v_cvt_pk_bf16_f32 v7, v4, v5
	global_store_dwordx2 v[0:1], v[6:7], off
	v_pk_mul_f32 v[6:7], v[28:29], v[2:3] op_sel_hi:[1,0]
	v_pk_mul_f32 v[4:5], v[26:27], v[2:3] op_sel_hi:[1,0]
	v_mul_f32_e32 v10, 0xbfb8aa3b, v6
	v_mul_f32_e32 v11, 0xbfb8aa3b, v7
	v_exp_f32_e32 v10, v10
	v_exp_f32_e32 v11, v11
	v_pk_mul_f32 v[2:3], v[32:33], v[2:3] op_sel_hi:[1,0]
	v_add_f32_e32 v10, 1.0, v10
	v_add_f32_e32 v11, 1.0, v11
	v_rcp_f32_e32 v10, v10
	v_rcp_f32_e32 v11, v11
	s_nop 0
	v_pk_mul_f32 v[6:7], v[6:7], v[10:11]
	s_nop 0
	v_pk_mul_f32 v[2:3], v[2:3], v[6:7]
	v_mul_f32_e32 v6, 0xbfb8aa3b, v4
	v_mul_f32_e32 v7, 0xbfb8aa3b, v5
	v_exp_f32_e32 v6, v6
	v_exp_f32_e32 v7, v7
	v_cvt_pk_bf16_f32 v2, v2, v3
	v_add_f32_e32 v6, 1.0, v6
	v_add_f32_e32 v7, 1.0, v7
	v_rcp_f32_e32 v6, v6
	v_rcp_f32_e32 v7, v7
	s_nop 0
	v_pk_mul_f32 v[4:5], v[4:5], v[6:7]
	s_nop 0
	v_pk_mul_f32 v[4:5], v[8:9], v[4:5]
	s_nop 0
	v_cvt_pk_bf16_f32 v3, v4, v5
	global_store_dwordx2 v[0:1], v[2:3], off offset:32
	s_branch .LBB0_293

; template <int MODE>
; __device__ __forceinline__ void small_gemm(const bf16_t* A, const bf16_t* Bt, int Npos, int K, const LAS unsigned long long* eap, LAS unsigned char* lds, int wg, int G, int wid, int lane) {
;     ...
;     for (int u = wg; u < nunits; u += G) {
;         const int rb = u % (TS / 16), cgp = u / (TS / 16), r0 = TP + rb * 16, p0 = cgp * 64;
;         f32x4 acc[4];
; #pragma unroll
;         for (int f = 0; f < 4; ++f) acc[f] = (f32x4){0.f, 0.f, 0.f, 0.f};
;         const bf16_t* ap = A + (size_t)(r0 + fr) * K + wid * KW + 8 * fq;
;         const bf16_t* bp = Bt + (size_t)(p0 + fr) * K + wid * KW + 8 * fq;
;         for (int k0 = 0; k0 < KW; k0 += 32) {
;             const bf16x8 av = *(const bf16x8*)(ap + k0);
;             bf16x8 wv[4];
; #pragma unroll
;             for (int f = 0; f < 4; ++f) wv[f] = *(const bf16x8*)(bp + (size_t)(16 * f) * K + k0);
; #pragma unroll
;             for (int f = 0; f < 4; ++f) acc[f] = __builtin_amdgcn_mfma_f32_16x16x32_bf16(wv[f], av, acc[f], 0, 0, 0);
;         }
; #pragma unroll
;         for (int f = 0; f < 4; ++f) part[(wid * 4 + f) * 64 + lane] = acc[f];
.LBB0_326:
	s_ashr_i32 s13, s12, 31
	s_lshr_b32 s13, s13, 29
	s_add_i32 s13, s12, s13
	s_ashr_i32 s28, s13, 3
	s_and_b32 s13, s13, 0xffffff8
	s_sub_i32 s14, s12, s13
	s_lshl_b32 s13, s28, 6
	v_or_b32_e32 v0, s13, v165
	v_lshlrev_b32_e32 v2, 1, v0
	v_lshl_add_u32 v160, s14, 4, v167
	v_or_b32_e32 v3, 32, v2
	v_or_b32_e32 v2, 64, v2
	v_ashrrev_i32_e32 v1, 31, v0
	v_mad_u64_u32 v[22:23], s[14:15], s4, v160, v[16:17]
	v_mad_i64_i32 v[24:25], s[14:15], s4, v0, v[18:19]
	v_mad_u64_u32 v[26:27], s[14:15], s48, v3, v[18:19]
	v_mad_u64_u32 v[28:29], s[14:15], s48, v2, v[18:19]
	v_mad_i64_i32 v[30:31], s[14:15], s4, v0, v[20:21]
	v_mov_b32_e32 v0, 0
	v_mad_i32_i24 v27, s48, v1, v27
	v_mad_i32_i24 v29, s48, v1, v29
	s_mov_b32 s14, 0
	v_mov_b32_e32 v1, v0
	v_mov_b32_e32 v2, v0
	v_mov_b32_e32 v3, v0
	v_mov_b32_e32 v12, v0
	v_mov_b32_e32 v13, v0
	v_mov_b32_e32 v14, v0
	v_mov_b32_e32 v15, v0
	v_mov_b32_e32 v4, v0
	v_mov_b32_e32 v5, v0
	v_mov_b32_e32 v6, v0
	v_mov_b32_e32 v7, v0
	v_mov_b32_e32 v8, v0
	v_mov_b32_e32 v9, v0
	v_mov_b32_e32 v10, v0
	v_mov_b32_e32 v11, v0
	s_cmpk_eq_u32 s96, 0x80
	s_cbranch_scc1 .Lsg_M2_k4
	s_cmpk_eq_u32 s96, 0x160
	s_cbranch_scc1 .Lsg_M2_k11
.LBB0_327:
	v_lshl_add_u64 v[40:41], v[22:23], 0, s[18:19]
	v_lshl_add_u64 v[36:37], v[24:25], 0, s[18:19]
	v_lshl_add_u64 v[44:45], v[26:27], 0, s[18:19]
	global_load_dwordx4 v[36:39], v[36:37], off
	s_nop 0
	global_load_dwordx4 v[40:43], v[40:41], off
	s_nop 0
	global_load_dwordx4 v[44:47], v[44:45], off
	v_lshl_add_u64 v[48:49], v[28:29], 0, s[18:19]
	v_lshl_add_u64 v[50:51], v[30:31], 0, s[18:19]
	s_add_i32 s14, s14, 32
	v_lshl_add_u64 v[22:23], v[22:23], 0, 64
	v_lshl_add_u64 v[24:25], v[24:25], 0, 64
	v_lshl_add_u64 v[26:27], v[26:27], 0, 64
	v_lshl_add_u64 v[28:29], v[28:29], 0, 64
	s_cmp_ge_u32 s14, s96
	v_lshl_add_u64 v[30:31], v[30:31], 0, 64
	s_waitcnt vmcnt(1)
	v_mfma_f32_16x16x32_bf16 v[12:15], v[36:39], v[40:43], v[12:15]
	global_load_dwordx4 v[36:39], v[48:49], off
	s_waitcnt vmcnt(1)
	v_mfma_f32_16x16x32_bf16 v[4:7], v[44:47], v[40:43], v[4:7]
	global_load_dwordx4 v[44:47], v[50:51], off
	s_waitcnt vmcnt(1)
	v_mfma_f32_16x16x32_bf16 v[8:11], v[36:39], v[40:43], v[8:11]
	s_waitcnt vmcnt(0)
	v_mfma_f32_16x16x32_bf16 v[0:3], v[44:47], v[40:43], v[0:3]
	s_cbranch_scc0 .LBB0_327
	s_branch .Lsg_M2_done
.Lsg_M2_k4:
	v_lshl_add_u64 v[52:53], v[22:23], 0, s[18:19]
	global_load_dwordx4 v[52:55], v[52:53], off offset:0
	v_lshl_add_u64 v[56:57], v[24:25], 0, s[18:19]
	global_load_dwordx4 v[56:59], v[56:57], off offset:0
	v_lshl_add_u64 v[60:61], v[26:27], 0, s[18:19]
	global_load_dwordx4 v[60:63], v[60:61], off offset:0
	v_lshl_add_u64 v[64:65], v[28:29], 0, s[18:19]
	global_load_dwordx4 v[64:67], v[64:65], off offset:0
	v_lshl_add_u64 v[68:69], v[30:31], 0, s[18:19]
	global_load_dwordx4 v[68:71], v[68:69], off offset:0
	v_lshl_add_u64 v[72:73], v[22:23], 0, s[18:19]
	global_load_dwordx4 v[72:75], v[72:73], off offset:64
	v_lshl_add_u64 v[76:77], v[24:25], 0, s[18:19]
	global_load_dwordx4 v[76:79], v[76:77], off offset:64
	v_lshl_add_u64 v[80:81], v[26:27], 0, s[18:19]
	global_load_dwordx4 v[80:83], v[80:81], off offset:64
	v_lshl_add_u64 v[84:85], v[28:29], 0, s[18:19]
	global_load_dwordx4 v[84:87], v[84:85], off offset:64
	v_lshl_add_u64 v[88:89], v[30:31], 0, s[18:19]
	global_load_dwordx4 v[88:91], v[88:89], off offset:64
	v_lshl_add_u64 v[92:93], v[22:23], 0, s[18:19]
	global_load_dwordx4 v[92:95], v[92:93], off offset:128
	v_lshl_add_u64 v[96:97], v[24:25], 0, s[18:19]
	global_load_dwordx4 v[96:99], v[96:97], off offset:128
	v_lshl_add_u64 v[100:101], v[26:27], 0, s[18:19]
	global_load_dwordx4 v[100:103], v[100:101], off offset:128
	v_lshl_add_u64 v[104:105], v[28:29], 0, s[18:19]
	global_load_dwordx4 v[104:107], v[104:105], off offset:128
	v_lshl_add_u64 v[108:109], v[30:31], 0, s[18:19]
	global_load_dwordx4 v[108:111], v[108:109], off offset:128
	v_lshl_add_u64 v[112:113], v[22:23], 0, s[18:19]
	global_load_dwordx4 v[112:115], v[112:113], off offset:192
	v_lshl_add_u64 v[116:117], v[24:25], 0, s[18:19]
	global_load_dwordx4 v[116:119], v[116:117], off offset:192
	v_lshl_add_u64 v[120:121], v[26:27], 0, s[18:19]
	global_load_dwordx4 v[120:123], v[120:121], off offset:192
	v_lshl_add_u64 v[124:125], v[28:29], 0, s[18:19]
	global_load_dwordx4 v[124:127], v[124:125], off offset:192
	v_lshl_add_u64 v[128:129], v[30:31], 0, s[18:19]
	global_load_dwordx4 v[128:131], v[128:129], off offset:192
	s_waitcnt vmcnt(18)
	v_mfma_f32_16x16x32_bf16 v[12:15], v[56:59], v[52:55], v[12:15]
	s_waitcnt vmcnt(17)
	v_mfma_f32_16x16x32_bf16 v[4:7], v[60:63], v[52:55], v[4:7]
	s_waitcnt vmcnt(16)
	v_mfma_f32_16x16x32_bf16 v[8:11], v[64:67], v[52:55], v[8:11]
	s_waitcnt vmcnt(15)
	v_mfma_f32_16x16x32_bf16 v[0:3], v[68:71], v[52:55], v[0:3]
	s_waitcnt vmcnt(13)
	v_mfma_f32_16x16x32_bf16 v[12:15], v[76:79], v[72:75], v[12:15]
	s_waitcnt vmcnt(12)
	v_mfma_f32_16x16x32_bf16 v[4:7], v[80:83], v[72:75], v[4:7]
	s_waitcnt vmcnt(11)
	v_mfma_f32_16x16x32_bf16 v[8:11], v[84:87], v[72:75], v[8:11]
	s_waitcnt vmcnt(10)
	v_mfma_f32_16x16x32_bf16 v[0:3], v[88:91], v[72:75], v[0:3]
	s_waitcnt vmcnt(8)
	v_mfma_f32_16x16x32_bf16 v[12:15], v[96:99], v[92:95], v[12:15]
	s_waitcnt vmcnt(7)
	v_mfma_f32_16x16x32_bf16 v[4:7], v[100:103], v[92:95], v[4:7]
	s_waitcnt vmcnt(6)
	v_mfma_f32_16x16x32_bf16 v[8:11], v[104:107], v[92:95], v[8:11]
	s_waitcnt vmcnt(5)
	v_mfma_f32_16x16x32_bf16 v[0:3], v[108:111], v[92:95], v[0:3]
	s_waitcnt vmcnt(3)
	v_mfma_f32_16x16x32_bf16 v[12:15], v[116:119], v[112:115], v[12:15]
	s_waitcnt vmcnt(2)
	v_mfma_f32_16x16x32_bf16 v[4:7], v[120:123], v[112:115], v[4:7]
	s_waitcnt vmcnt(1)
	v_mfma_f32_16x16x32_bf16 v[8:11], v[124:127], v[112:115], v[8:11]
	s_waitcnt vmcnt(0)
	v_mfma_f32_16x16x32_bf16 v[0:3], v[128:131], v[112:115], v[0:3]
	s_branch .Lsg_M2_done
; template <int MODE>
; __device__ __forceinline__ void small_gemm(const bf16_t* A, const bf16_t* Bt, int Npos, int K, const LAS unsigned long long* eap, LAS unsigned char* lds, int wg, int G, int wid, int lane) {
;     ...
;         for (int k0 = 0; k0 < KW; k0 += 32) {
;             const bf16x8 av = *(const bf16x8*)(ap + k0);
;             bf16x8 wv[4];
; #pragma unroll
;             for (int f = 0; f < 4; ++f) wv[f] = *(const bf16x8*)(bp + (size_t)(16 * f) * K + k0);
; #pragma unroll
;             for (int f = 0; f < 4; ++f) acc[f] = __builtin_amdgcn_mfma_f32_16x16x32_bf16(wv[f], av, acc[f], 0, 0, 0);
;         }
.Lsg_M2_k11:
	v_lshl_add_u64 v[52:53], v[22:23], 0, s[18:19]
	global_load_dwordx4 v[52:55], v[52:53], off offset:0
	v_lshl_add_u64 v[56:57], v[24:25], 0, s[18:19]
	global_load_dwordx4 v[56:59], v[56:57], off offset:0
	v_lshl_add_u64 v[60:61], v[26:27], 0, s[18:19]
	global_load_dwordx4 v[60:63], v[60:61], off offset:0
	v_lshl_add_u64 v[64:65], v[28:29], 0, s[18:19]
	global_load_dwordx4 v[64:67], v[64:65], off offset:0
	v_lshl_add_u64 v[68:69], v[30:31], 0, s[18:19]
	global_load_dwordx4 v[68:71], v[68:69], off offset:0
	v_lshl_add_u64 v[72:73], v[22:23], 0, s[18:19]
	global_load_dwordx4 v[72:75], v[72:73], off offset:64
	v_lshl_add_u64 v[76:77], v[24:25], 0, s[18:19]
	global_load_dwordx4 v[76:79], v[76:77], off offset:64
	v_lshl_add_u64 v[80:81], v[26:27], 0, s[18:19]
	global_load_dwordx4 v[80:83], v[80:81], off offset:64
	v_lshl_add_u64 v[84:85], v[28:29], 0, s[18:19]
	global_load_dwordx4 v[84:87], v[84:85], off offset:64
	v_lshl_add_u64 v[88:89], v[30:31], 0, s[18:19]
	global_load_dwordx4 v[88:91], v[88:89], off offset:64
	v_lshl_add_u64 v[92:93], v[22:23], 0, s[18:19]
	global_load_dwordx4 v[92:95], v[92:93], off offset:128
	v_lshl_add_u64 v[96:97], v[24:25], 0, s[18:19]
	global_load_dwordx4 v[96:99], v[96:97], off offset:128
	v_lshl_add_u64 v[100:101], v[26:27], 0, s[18:19]
	global_load_dwordx4 v[100:103], v[100:101], off offset:128
	v_lshl_add_u64 v[104:105], v[28:29], 0, s[18:19]
	global_load_dwordx4 v[104:107], v[104:105], off offset:128
	v_lshl_add_u64 v[108:109], v[30:31], 0, s[18:19]
	global_load_dwordx4 v[108:111], v[108:109], off offset:128
	v_lshl_add_u64 v[112:113], v[22:23], 0, s[18:19]
	global_load_dwordx4 v[112:115], v[112:113], off offset:192
	v_lshl_add_u64 v[116:117], v[24:25], 0, s[18:19]
	global_load_dwordx4 v[116:119], v[116:117], off offset:192
	v_lshl_add_u64 v[120:121], v[26:27], 0, s[18:19]
	global_load_dwordx4 v[120:123], v[120:121], off offset:192
	v_lshl_add_u64 v[124:125], v[28:29], 0, s[18:19]
	global_load_dwordx4 v[124:127], v[124:125], off offset:192
	v_lshl_add_u64 v[128:129], v[30:31], 0, s[18:19]
	global_load_dwordx4 v[128:131], v[128:129], off offset:192
	v_lshl_add_u64 v[132:133], v[22:23], 0, s[18:19]
	global_load_dwordx4 v[132:135], v[132:133], off offset:256
	v_lshl_add_u64 v[136:137], v[24:25], 0, s[18:19]
	global_load_dwordx4 v[136:139], v[136:137], off offset:256
	v_lshl_add_u64 v[140:141], v[26:27], 0, s[18:19]
	global_load_dwordx4 v[140:143], v[140:141], off offset:256
	v_lshl_add_u64 v[144:145], v[28:29], 0, s[18:19]
	global_load_dwordx4 v[144:147], v[144:145], off offset:256
	v_lshl_add_u64 v[148:149], v[30:31], 0, s[18:19]
	global_load_dwordx4 v[148:151], v[148:149], off offset:256
	s_waitcnt vmcnt(23)
	v_mfma_f32_16x16x32_bf16 v[12:15], v[56:59], v[52:55], v[12:15]
	v_lshl_add_u64 v[56:57], v[22:23], 0, s[18:19]
	global_load_dwordx4 v[56:59], v[56:57], off offset:320
	s_waitcnt vmcnt(23)
	v_mfma_f32_16x16x32_bf16 v[4:7], v[60:63], v[52:55], v[4:7]
	v_lshl_add_u64 v[60:61], v[24:25], 0, s[18:19]
	global_load_dwordx4 v[60:63], v[60:61], off offset:320
	s_waitcnt vmcnt(23)
	v_mfma_f32_16x16x32_bf16 v[8:11], v[64:67], v[52:55], v[8:11]
	v_lshl_add_u64 v[64:65], v[26:27], 0, s[18:19]
	global_load_dwordx4 v[64:67], v[64:65], off offset:320
	s_waitcnt vmcnt(23)
	v_mfma_f32_16x16x32_bf16 v[0:3], v[68:71], v[52:55], v[0:3]
	v_lshl_add_u64 v[68:69], v[28:29], 0, s[18:19]
	global_load_dwordx4 v[68:71], v[68:69], off offset:320
	v_lshl_add_u64 v[52:53], v[30:31], 0, s[18:19]
	global_load_dwordx4 v[52:55], v[52:53], off offset:320
	s_waitcnt vmcnt(23)
	v_mfma_f32_16x16x32_bf16 v[12:15], v[76:79], v[72:75], v[12:15]
	v_lshl_add_u64 v[76:77], v[22:23], 0, s[18:19]
	global_load_dwordx4 v[76:79], v[76:77], off offset:384
	s_waitcnt vmcnt(23)
	v_mfma_f32_16x16x32_bf16 v[4:7], v[80:83], v[72:75], v[4:7]
	v_lshl_add_u64 v[80:81], v[24:25], 0, s[18:19]
	global_load_dwordx4 v[80:83], v[80:81], off offset:384
	s_waitcnt vmcnt(23)
	v_mfma_f32_16x16x32_bf16 v[8:11], v[84:87], v[72:75], v[8:11]
	v_lshl_add_u64 v[84:85], v[26:27], 0, s[18:19]
	global_load_dwordx4 v[84:87], v[84:85], off offset:384
	s_waitcnt vmcnt(23)
	v_mfma_f32_16x16x32_bf16 v[0:3], v[88:91], v[72:75], v[0:3]
	v_lshl_add_u64 v[88:89], v[28:29], 0, s[18:19]
	global_load_dwordx4 v[88:91], v[88:89], off offset:384
	v_lshl_add_u64 v[72:73], v[30:31], 0, s[18:19]
	global_load_dwordx4 v[72:75], v[72:73], off offset:384
	s_waitcnt vmcnt(23)
	v_mfma_f32_16x16x32_bf16 v[12:15], v[96:99], v[92:95], v[12:15]
	v_lshl_add_u64 v[96:97], v[22:23], 0, s[18:19]
	global_load_dwordx4 v[96:99], v[96:97], off offset:448
	s_waitcnt vmcnt(23)
	v_mfma_f32_16x16x32_bf16 v[4:7], v[100:103], v[92:95], v[4:7]
	v_lshl_add_u64 v[100:101], v[24:25], 0, s[18:19]
	global_load_dwordx4 v[100:103], v[100:101], off offset:448
	s_waitcnt vmcnt(23)
	v_mfma_f32_16x16x32_bf16 v[8:11], v[104:107], v[92:95], v[8:11]
	v_lshl_add_u64 v[104:105], v[26:27], 0, s[18:19]
	global_load_dwordx4 v[104:107], v[104:105], off offset:448
	s_waitcnt vmcnt(23)
	v_mfma_f32_16x16x32_bf16 v[0:3], v[108:111], v[92:95], v[0:3]
	v_lshl_add_u64 v[108:109], v[28:29], 0, s[18:19]
	global_load_dwordx4 v[108:111], v[108:109], off offset:448
	v_lshl_add_u64 v[92:93], v[30:31], 0, s[18:19]
	global_load_dwordx4 v[92:95], v[92:93], off offset:448
	s_waitcnt vmcnt(23)
	v_mfma_f32_16x16x32_bf16 v[12:15], v[116:119], v[112:115], v[12:15]
	v_lshl_add_u64 v[116:117], v[22:23], 0, s[18:19]
	global_load_dwordx4 v[116:119], v[116:117], off offset:512
	s_waitcnt vmcnt(23)
	v_mfma_f32_16x16x32_bf16 v[4:7], v[120:123], v[112:115], v[4:7]
	v_lshl_add_u64 v[120:121], v[24:25], 0, s[18:19]
	global_load_dwordx4 v[120:123], v[120:121], off offset:512
	s_waitcnt vmcnt(23)
; template <int MODE>
; __device__ __forceinline__ void small_gemm(const bf16_t* A, const bf16_t* Bt, int Npos, int K, const LAS unsigned long long* eap, LAS unsigned char* lds, int wg, int G, int wid, int lane) {
;     ...
;         for (int k0 = 0; k0 < KW; k0 += 32) {
;             const bf16x8 av = *(const bf16x8*)(ap + k0);
;             bf16x8 wv[4];
; #pragma unroll
;             for (int f = 0; f < 4; ++f) wv[f] = *(const bf16x8*)(bp + (size_t)(16 * f) * K + k0);
; #pragma unroll
;             for (int f = 0; f < 4; ++f) acc[f] = __builtin_amdgcn_mfma_f32_16x16x32_bf16(wv[f], av, acc[f], 0, 0, 0);
;         }
; #pragma unroll
;         for (int f = 0; f < 4; ++f) part[(wid * 4 + f) * 64 + lane] = acc[f];
;         __syncthreads();
	v_mfma_f32_16x16x32_bf16 v[8:11], v[124:127], v[112:115], v[8:11]
	v_lshl_add_u64 v[124:125], v[26:27], 0, s[18:19]
	global_load_dwordx4 v[124:127], v[124:125], off offset:512
	s_waitcnt vmcnt(23)
	v_mfma_f32_16x16x32_bf16 v[0:3], v[128:131], v[112:115], v[0:3]
	v_lshl_add_u64 v[128:129], v[28:29], 0, s[18:19]
	global_load_dwordx4 v[128:131], v[128:129], off offset:512
	v_lshl_add_u64 v[112:113], v[30:31], 0, s[18:19]
	global_load_dwordx4 v[112:115], v[112:113], off offset:512
	s_waitcnt vmcnt(23)
	v_mfma_f32_16x16x32_bf16 v[12:15], v[136:139], v[132:135], v[12:15]
	v_lshl_add_u64 v[136:137], v[22:23], 0, s[18:19]
	global_load_dwordx4 v[136:139], v[136:137], off offset:576
	s_waitcnt vmcnt(23)
	v_mfma_f32_16x16x32_bf16 v[4:7], v[140:143], v[132:135], v[4:7]
	v_lshl_add_u64 v[140:141], v[24:25], 0, s[18:19]
	global_load_dwordx4 v[140:143], v[140:141], off offset:576
	s_waitcnt vmcnt(23)
	v_mfma_f32_16x16x32_bf16 v[8:11], v[144:147], v[132:135], v[8:11]
	v_lshl_add_u64 v[144:145], v[26:27], 0, s[18:19]
	global_load_dwordx4 v[144:147], v[144:145], off offset:576
	s_waitcnt vmcnt(23)
	v_mfma_f32_16x16x32_bf16 v[0:3], v[148:151], v[132:135], v[0:3]
	v_lshl_add_u64 v[148:149], v[28:29], 0, s[18:19]
	global_load_dwordx4 v[148:151], v[148:149], off offset:576
	v_lshl_add_u64 v[132:133], v[30:31], 0, s[18:19]
	global_load_dwordx4 v[132:135], v[132:133], off offset:576
	s_waitcnt vmcnt(23)
	v_mfma_f32_16x16x32_bf16 v[12:15], v[60:63], v[56:59], v[12:15]
	v_lshl_add_u64 v[60:61], v[22:23], 0, s[18:19]
	global_load_dwordx4 v[60:63], v[60:61], off offset:640
	s_waitcnt vmcnt(23)
	v_mfma_f32_16x16x32_bf16 v[4:7], v[64:67], v[56:59], v[4:7]
	v_lshl_add_u64 v[64:65], v[24:25], 0, s[18:19]
	global_load_dwordx4 v[64:67], v[64:65], off offset:640
	s_waitcnt vmcnt(23)
	v_mfma_f32_16x16x32_bf16 v[8:11], v[68:71], v[56:59], v[8:11]
	v_lshl_add_u64 v[68:69], v[26:27], 0, s[18:19]
	global_load_dwordx4 v[68:71], v[68:69], off offset:640
	s_waitcnt vmcnt(23)
	v_mfma_f32_16x16x32_bf16 v[0:3], v[52:55], v[56:59], v[0:3]
	v_lshl_add_u64 v[52:53], v[28:29], 0, s[18:19]
	global_load_dwordx4 v[52:55], v[52:53], off offset:640
	v_lshl_add_u64 v[56:57], v[30:31], 0, s[18:19]
	global_load_dwordx4 v[56:59], v[56:57], off offset:640
	s_waitcnt vmcnt(23)
	v_mfma_f32_16x16x32_bf16 v[12:15], v[80:83], v[76:79], v[12:15]
	s_waitcnt vmcnt(22)
	v_mfma_f32_16x16x32_bf16 v[4:7], v[84:87], v[76:79], v[4:7]
	s_waitcnt vmcnt(21)
	v_mfma_f32_16x16x32_bf16 v[8:11], v[88:91], v[76:79], v[8:11]
	s_waitcnt vmcnt(20)
	v_mfma_f32_16x16x32_bf16 v[0:3], v[72:75], v[76:79], v[0:3]
	s_waitcnt vmcnt(18)
	v_mfma_f32_16x16x32_bf16 v[12:15], v[100:103], v[96:99], v[12:15]
	s_waitcnt vmcnt(17)
	v_mfma_f32_16x16x32_bf16 v[4:7], v[104:107], v[96:99], v[4:7]
	s_waitcnt vmcnt(16)
	v_mfma_f32_16x16x32_bf16 v[8:11], v[108:111], v[96:99], v[8:11]
	s_waitcnt vmcnt(15)
	v_mfma_f32_16x16x32_bf16 v[0:3], v[92:95], v[96:99], v[0:3]
	s_waitcnt vmcnt(13)
	v_mfma_f32_16x16x32_bf16 v[12:15], v[120:123], v[116:119], v[12:15]
	s_waitcnt vmcnt(12)
	v_mfma_f32_16x16x32_bf16 v[4:7], v[124:127], v[116:119], v[4:7]
	s_waitcnt vmcnt(11)
	v_mfma_f32_16x16x32_bf16 v[8:11], v[128:131], v[116:119], v[8:11]
	s_waitcnt vmcnt(10)
	v_mfma_f32_16x16x32_bf16 v[0:3], v[112:115], v[116:119], v[0:3]
	s_waitcnt vmcnt(8)
	v_mfma_f32_16x16x32_bf16 v[12:15], v[140:143], v[136:139], v[12:15]
	s_waitcnt vmcnt(7)
	v_mfma_f32_16x16x32_bf16 v[4:7], v[144:147], v[136:139], v[4:7]
	s_waitcnt vmcnt(6)
	v_mfma_f32_16x16x32_bf16 v[8:11], v[148:151], v[136:139], v[8:11]
	s_waitcnt vmcnt(5)
	v_mfma_f32_16x16x32_bf16 v[0:3], v[132:135], v[136:139], v[0:3]
	s_waitcnt vmcnt(3)
	v_mfma_f32_16x16x32_bf16 v[12:15], v[64:67], v[60:63], v[12:15]
	s_waitcnt vmcnt(2)
	v_mfma_f32_16x16x32_bf16 v[4:7], v[68:71], v[60:63], v[4:7]
	s_waitcnt vmcnt(1)
	v_mfma_f32_16x16x32_bf16 v[8:11], v[52:55], v[60:63], v[8:11]
	s_waitcnt vmcnt(0)
	v_mfma_f32_16x16x32_bf16 v[0:3], v[56:59], v[60:63], v[0:3]
.Lsg_M2_done:
	v_add_u32_e32 v22, s2, v33
	s_and_b64 vcc, exec, s[0:1]
	ds_write_b128 v22, v[12:15]
	ds_write_b128 v22, v[4:7] offset:1024
	s_nop 0
	ds_write_b128 v22, v[8:11] offset:2048
	s_nop 0
	ds_write_b128 v22, v[0:3] offset:3072
	s_waitcnt lgkmcnt(0)
	s_barrier
	s_cbranch_vccz .LBB0_325
; #define GAS __attribute__((address_space(1)))
; __device__ __forceinline__ unsigned pk2(float lo, float hi) { const f32x2 v = {lo, hi}; return __builtin_bit_cast(unsigned, __builtin_convertvector(v, hwbf16x2)); }
; template <int MODE, bool SMALL>
; __device__ __forceinline__ float epi_apply(const EpiArgs& a, int row, int g32, int fq, f32x4 v0, f32x4 v1, float rstd) {
;     ...
;         GAS u32x4* xp = (GAS u32x4*)(a.Xb + (size_t)row * DM + c0);
;         const u32x4 bw = *xp;
;         f32x4 x0, x1;
;         x0[0] = __builtin_bit_cast(float, bw[0] << 16) + v0[0]; x0[1] = __builtin_bit_cast(float, bw[0] & 0xffff0000u) + v0[1]; x0[2] = __builtin_bit_cast(float, bw[1] << 16) + v0[2]; x0[3] = __builtin_bit_cast(float, bw[1] & 0xffff0000u) + v0[3];
;         x1[0] = __builtin_bit_cast(float, bw[2] << 16) + v1[0]; x1[1] = __builtin_bit_cast(float, bw[2] & 0xffff0000u) + v1[1]; x1[2] = __builtin_bit_cast(float, bw[3] << 16) + v1[2]; x1[3] = __builtin_bit_cast(float, bw[3] & 0xffff0000u) + v1[3];
;         u32x4 w; w.x = pk2(x0[0], x0[1]); w.y = pk2(x0[2], x0[3]); w.z = pk2(x1[0], x1[1]); w.w = pk2(x1[2], x1[3]);
;         *xp = w;
;         return ((x0[0] * x0[0] + x0[1] * x0[1]) + (x0[2] * x0[2] + x0[3] * x0[3])) + ((x1[0] * x1[0] + x1[1] * x1[1]) + (x1[2] * x1[2] + x1[3] * x1[3]));
; template <int MODE>
; __device__ __forceinline__ void small_gemm(const bf16_t* A, const bf16_t* Bt, int Npos, int K, const LAS unsigned long long* eap, LAS unsigned char* lds, int wg, int G, int wid, int lane) {
;     ...
;         if (wid == 0) {
; #pragma unroll
;             for (int w = 1; w < 8; ++w)
; #pragma unroll
;                 for (int f = 0; f < 4; ++f) acc[f] += part[(w * 4 + f) * 64 + lane];
;             const int row = r0 + fr;
;             const EpiArgs a = load_ea(eap);
;             float rstd = 1.f; if constexpr (MODE != 2) rstd = row_rstd(a.ssp, row);
;             float ss = 0.f;
; #pragma unroll
;             for (int gq = 0; gq < 2; ++gq) ss += epi_apply<MODE, true>(a, row, (p0 >> 5) + gq, fq, acc[2 * gq], acc[2 * gq + 1], rstd);
;             if constexpr (MODE == 2) { ss += __shfl_xor(ss, 16); ss += __shfl_xor(ss, 32); if (fq == 0) a.ssp_out[(size_t)row * 16 + cgp] = ss; }
	ds_read_b128 v[22:25], v33 offset:4096
	v_readlane_b32 s14, v245, 11
	s_waitcnt lgkmcnt(0)
	v_pk_add_f32 v[24:25], v[14:15], v[24:25]
	v_pk_add_f32 v[22:23], v[12:13], v[22:23]
	ds_read_b128 v[12:15], v33 offset:5120
	s_waitcnt lgkmcnt(0)
	v_pk_add_f32 v[14:15], v[6:7], v[14:15]
	v_pk_add_f32 v[12:13], v[4:5], v[12:13]
	ds_read_b128 v[4:7], v33 offset:6144
	s_waitcnt lgkmcnt(0)
	v_pk_add_f32 v[10:11], v[10:11], v[6:7]
	v_pk_add_f32 v[8:9], v[8:9], v[4:5]
	ds_read_b128 v[4:7], v33 offset:7168
	s_waitcnt lgkmcnt(0)
	v_pk_add_f32 v[6:7], v[2:3], v[6:7]
	v_pk_add_f32 v[4:5], v[0:1], v[4:5]
	ds_read_b128 v[0:3], v33 offset:8192
	s_waitcnt lgkmcnt(0)
	v_pk_add_f32 v[24:25], v[24:25], v[2:3]
	v_pk_add_f32 v[22:23], v[22:23], v[0:1]
	ds_read_b128 v[0:3], v33 offset:9216
	s_waitcnt lgkmcnt(0)
	v_pk_add_f32 v[14:15], v[14:15], v[2:3]
	v_pk_add_f32 v[12:13], v[12:13], v[0:1]
	ds_read_b128 v[0:3], v33 offset:10240
	s_waitcnt lgkmcnt(0)
	v_pk_add_f32 v[10:11], v[10:11], v[2:3]
	v_pk_add_f32 v[8:9], v[8:9], v[0:1]
	ds_read_b128 v[0:3], v33 offset:11264
	s_waitcnt lgkmcnt(0)
	v_pk_add_f32 v[6:7], v[6:7], v[2:3]
	v_pk_add_f32 v[4:5], v[4:5], v[0:1]
	ds_read_b128 v[0:3], v33 offset:12288
	s_waitcnt lgkmcnt(0)
	v_pk_add_f32 v[24:25], v[24:25], v[2:3]
	v_pk_add_f32 v[22:23], v[22:23], v[0:1]
	ds_read_b128 v[0:3], v33 offset:13312
	s_waitcnt lgkmcnt(0)
	v_pk_add_f32 v[14:15], v[14:15], v[2:3]
	v_pk_add_f32 v[12:13], v[12:13], v[0:1]
	ds_read_b128 v[0:3], v33 offset:14336
	s_waitcnt lgkmcnt(0)
	v_pk_add_f32 v[10:11], v[10:11], v[2:3]
	v_pk_add_f32 v[8:9], v[8:9], v[0:1]
	ds_read_b128 v[0:3], v33 offset:15360
	s_waitcnt lgkmcnt(0)
	v_pk_add_f32 v[6:7], v[6:7], v[2:3]
	v_pk_add_f32 v[4:5], v[4:5], v[0:1]
	ds_read_b128 v[0:3], v33 offset:16384
	s_waitcnt lgkmcnt(0)
	v_pk_add_f32 v[24:25], v[24:25], v[2:3]
	v_pk_add_f32 v[22:23], v[22:23], v[0:1]
	ds_read_b128 v[0:3], v33 offset:17408
	s_waitcnt lgkmcnt(0)
	v_pk_add_f32 v[14:15], v[14:15], v[2:3]
	v_pk_add_f32 v[12:13], v[12:13], v[0:1]
	ds_read_b128 v[0:3], v33 offset:18432
	s_waitcnt lgkmcnt(0)
	v_pk_add_f32 v[10:11], v[10:11], v[2:3]
	v_pk_add_f32 v[8:9], v[8:9], v[0:1]
	ds_read_b128 v[0:3], v33 offset:19456
	s_waitcnt lgkmcnt(0)
	v_pk_add_f32 v[6:7], v[6:7], v[2:3]
	v_pk_add_f32 v[4:5], v[4:5], v[0:1]
	ds_read_b128 v[0:3], v33 offset:20480
	s_waitcnt lgkmcnt(0)
	v_pk_add_f32 v[24:25], v[24:25], v[2:3]
	v_pk_add_f32 v[22:23], v[22:23], v[0:1]
	ds_read_b128 v[0:3], v33 offset:21504
	s_waitcnt lgkmcnt(0)
	v_pk_add_f32 v[14:15], v[14:15], v[2:3]
	v_pk_add_f32 v[12:13], v[12:13], v[0:1]
	ds_read_b128 v[0:3], v33 offset:22528
	s_waitcnt lgkmcnt(0)
	v_pk_add_f32 v[10:11], v[10:11], v[2:3]
	v_pk_add_f32 v[8:9], v[8:9], v[0:1]
	ds_read_b128 v[0:3], v33 offset:23552
	s_waitcnt lgkmcnt(0)
	v_pk_add_f32 v[6:7], v[6:7], v[2:3]
	v_pk_add_f32 v[4:5], v[4:5], v[0:1]
	ds_read_b128 v[0:3], v33 offset:24576
	s_waitcnt lgkmcnt(0)
	v_pk_add_f32 v[24:25], v[24:25], v[2:3]
	v_pk_add_f32 v[22:23], v[22:23], v[0:1]
	ds_read_b128 v[0:3], v33 offset:25600
	s_waitcnt lgkmcnt(0)
	v_pk_add_f32 v[14:15], v[14:15], v[2:3]
	v_pk_add_f32 v[12:13], v[12:13], v[0:1]
	ds_read_b128 v[0:3], v33 offset:26624
	s_waitcnt lgkmcnt(0)
	v_pk_add_f32 v[10:11], v[10:11], v[2:3]
	v_pk_add_f32 v[8:9], v[8:9], v[0:1]
	ds_read_b128 v[0:3], v33 offset:27648
	s_waitcnt lgkmcnt(0)
	v_pk_add_f32 v[26:27], v[6:7], v[2:3]
	v_pk_add_f32 v[28:29], v[4:5], v[0:1]
	ds_read_b128 v[0:3], v33 offset:28672
	s_waitcnt lgkmcnt(0)
	v_pk_add_f32 v[6:7], v[24:25], v[2:3]
	v_pk_add_f32 v[24:25], v[22:23], v[0:1]
	ds_read_b128 v[0:3], v33 offset:29696
	s_waitcnt lgkmcnt(0)
	v_pk_add_f32 v[4:5], v[14:15], v[2:3]
	v_pk_add_f32 v[22:23], v[12:13], v[0:1]
	ds_read_b128 v[0:3], v33 offset:30720
	s_waitcnt lgkmcnt(0)
	v_pk_add_f32 v[12:13], v[10:11], v[2:3]
	v_pk_add_f32 v[14:15], v[8:9], v[0:1]
	ds_read_b128 v[0:3], v33 offset:31744
	s_waitcnt lgkmcnt(0)
	v_pk_add_f32 v[10:11], v[28:29], v[0:1]
	v_mov_b32_e32 v0, s14
	v_pk_add_f32 v[8:9], v[26:27], v[2:3]
	ds_read_b128 v[0:3], v0
	v_or_b32_e32 v26, s13, v34
	v_lshlrev_b32_e32 v28, 11, v160
	v_mov_b32_e32 v29, v161
	v_ashrrev_i32_e32 v27, 31, v26
	s_waitcnt lgkmcnt(0)
	v_lshl_add_u64 v[0:1], v[0:1], 0, v[28:29]
	v_lshl_add_u64 v[28:29], v[26:27], 1, v[0:1]
	global_load_dwordx4 v[36:39], v[28:29], off
	s_waitcnt vmcnt(0)
	v_lshlrev_b32_e32 v0, 16, v36
	v_and_b32_e32 v1, 0xffff0000, v36
	v_pk_add_f32 v[0:1], v[24:25], v[0:1]
	v_lshlrev_b32_e32 v24, 16, v37
	v_and_b32_e32 v25, 0xffff0000, v37
	v_pk_add_f32 v[24:25], v[6:7], v[24:25]
	v_lshlrev_b32_e32 v6, 16, v38
	v_and_b32_e32 v7, 0xffff0000, v38
	v_pk_add_f32 v[26:27], v[22:23], v[6:7]
	v_lshlrev_b32_e32 v6, 16, v39
	v_and_b32_e32 v7, 0xffff0000, v39
	v_pk_add_f32 v[30:31], v[4:5], v[6:7]
	v_cvt_pk_bf16_f32 v4, v0, v1
	v_cvt_pk_bf16_f32 v5, v24, v25
	v_cvt_pk_bf16_f32 v6, v26, v27
	v_cvt_pk_bf16_f32 v7, v30, v31
	global_store_dwordx4 v[28:29], v[4:7], off
	global_load_dwordx4 v[4:7], v[28:29], off offset:64
	v_pk_mul_f32 v[22:23], v[24:25], v[24:25]
	v_pk_mul_f32 v[24:25], v[26:27], v[26:27]
	v_pk_mul_f32 v[26:27], v[30:31], v[30:31]
	v_pk_mul_f32 v[0:1], v[0:1], v[0:1]
	s_waitcnt vmcnt(0)
	v_lshlrev_b32_e32 v30, 16, v4
	v_and_b32_e32 v31, 0xffff0000, v4
	v_lshlrev_b32_e32 v4, 16, v5
	v_and_b32_e32 v5, 0xffff0000, v5
	v_pk_add_f32 v[12:13], v[12:13], v[4:5]
	v_lshlrev_b32_e32 v4, 16, v6
	v_and_b32_e32 v5, 0xffff0000, v6
	v_pk_add_f32 v[10:11], v[10:11], v[4:5]
	v_lshlrev_b32_e32 v4, 16, v7
	v_and_b32_e32 v5, 0xffff0000, v7
	v_pk_add_f32 v[14:15], v[14:15], v[30:31]
	v_pk_add_f32 v[8:9], v[8:9], v[4:5]
	v_cvt_pk_bf16_f32 v4, v14, v15
	v_cvt_pk_bf16_f32 v5, v12, v13
	v_cvt_pk_bf16_f32 v6, v10, v11
	v_cvt_pk_bf16_f32 v7, v8, v9
	global_store_dwordx4 v[28:29], v[4:7], off offset:64
	v_pk_mul_f32 v[10:11], v[10:11], v[10:11]
	v_pk_mul_f32 v[8:9], v[8:9], v[8:9]
	v_pk_mul_f32 v[4:5], v[14:15], v[14:15]
	v_pk_mul_f32 v[6:7], v[12:13], v[12:13]
	v_add_f32_e32 v12, v26, v27
	v_add_f32_e32 v13, v24, v25
	v_add_f32_e32 v12, v13, v12
	v_add_f32_e32 v13, v22, v23
	v_add_f32_e32 v0, v0, v1
	v_add_f32_e32 v1, v8, v9
	v_add_f32_e32 v8, v10, v11
	v_add_f32_e32 v6, v6, v7
	v_add_f32_e32 v4, v4, v5
	v_add_f32_e32 v0, v0, v13
	v_add_f32_e32 v1, v8, v1
	v_add_f32_e32 v4, v4, v6
	v_add_f32_e32 v0, v0, v12
	v_add_f32_e32 v1, v4, v1
	v_and_b32_e32 v4, 64, v200
	v_add_f32_e32 v0, v0, v1
	v_xor_b32_e32 v1, 16, v200
	v_add_u32_e32 v4, 64, v4
	v_cmp_lt_i32_e32 vcc, v1, v4
	s_nop 1
	v_cndmask_b32_e32 v1, v200, v1, vcc
	v_lshlrev_b32_e32 v1, 2, v1
	ds_bpermute_b32 v1, v1, v0
	s_waitcnt lgkmcnt(0)
	v_add_f32_e32 v0, v0, v1
	v_xor_b32_e32 v1, 32, v200
	v_cmp_lt_i32_e32 vcc, v1, v4
	s_nop 1
	v_cndmask_b32_e32 v1, v200, v1, vcc
	v_lshlrev_b32_e32 v1, 2, v1
	ds_bpermute_b32 v1, v1, v0
	s_and_saveexec_b64 s[34:35], s[38:39]
	s_cbranch_execz .LBB0_324
	s_waitcnt lgkmcnt(0)
	v_add_f32_e32 v4, v0, v1
	v_lshlrev_b64 v[0:1], 6, v[160:161]
	v_lshl_add_u64 v[0:1], v[2:3], 0, v[0:1]
	s_ashr_i32 s29, s28, 31
	v_lshl_add_u64 v[0:1], s[28:29], 2, v[0:1]
	global_store_dword v[0:1], v4, off
	s_branch .LBB0_324

; template <int MODE>
; __device__ __forceinline__ void small_gemm(const bf16_t* A, const bf16_t* Bt, int Npos, int K, const LAS unsigned long long* eap, LAS unsigned char* lds, int wg, int G, int wid, int lane) {
;     ...
;         const int rb = u % (TS / 16), cgp = u / (TS / 16), r0 = TP + rb * 16, p0 = cgp * 64;
;         f32x4 acc[4];
; #pragma unroll
;         for (int f = 0; f < 4; ++f) acc[f] = (f32x4){0.f, 0.f, 0.f, 0.f};
;         const bf16_t* ap = A + (size_t)(r0 + fr) * K + wid * KW + 8 * fq;
;         const bf16_t* bp = Bt + (size_t)(p0 + fr) * K + wid * KW + 8 * fq;
;         for (int k0 = 0; k0 < KW; k0 += 32) {
;             const bf16x8 av = *(const bf16x8*)(ap + k0);
;             bf16x8 wv[4];
; #pragma unroll
;             for (int f = 0; f < 4; ++f) wv[f] = *(const bf16x8*)(bp + (size_t)(16 * f) * K + k0);
; #pragma unroll
;             for (int f = 0; f < 4; ++f) acc[f] = __builtin_amdgcn_mfma_f32_16x16x32_bf16(wv[f], av, acc[f], 0, 0, 0);
;         }
; #pragma unroll
;         for (int f = 0; f < 4; ++f) part[(wid * 4 + f) * 64 + lane] = acc[f];
;         __syncthreads();
.LBB0_376:
	s_ashr_i32 s13, s12, 31
	s_lshr_b32 s13, s13, 29
	s_add_i32 s13, s12, s13
	s_and_b32 s14, s13, 0xffffff8
	s_lshl_b32 s13, s13, 3
	s_andn2_b32 s13, s13, 63
	v_or_b32_e32 v0, s13, v165
	s_sub_i32 s14, s12, s14
	v_lshlrev_b32_e32 v2, 1, v0
	v_lshl_add_u32 v160, s14, 4, v167
	v_or_b32_e32 v3, 32, v2
	v_or_b32_e32 v2, 64, v2
	v_ashrrev_i32_e32 v1, 31, v0
	s_waitcnt vmcnt(2)
	v_mad_u64_u32 v[16:17], s[14:15], s4, v160, v[72:73]
	v_mad_i64_i32 v[18:19], s[14:15], s4, v0, v[74:75]
	s_waitcnt vmcnt(0)
	v_mad_u64_u32 v[20:21], s[14:15], s48, v3, v[74:75]
	v_mad_u64_u32 v[22:23], s[14:15], s48, v2, v[74:75]
	v_mad_i64_i32 v[24:25], s[14:15], s4, v0, v[76:77]
	v_mov_b32_e32 v0, 0
	v_mad_i32_i24 v21, s48, v1, v21
	v_mad_i32_i24 v23, s48, v1, v23
	s_mov_b32 s14, 0
	v_mov_b32_e32 v1, v0
	v_mov_b32_e32 v2, v0
	v_mov_b32_e32 v3, v0
	v_mov_b32_e32 v8, v0
	v_mov_b32_e32 v9, v0
	v_mov_b32_e32 v10, v0
	v_mov_b32_e32 v11, v0
	v_mov_b32_e32 v12, v0
	v_mov_b32_e32 v13, v0
	v_mov_b32_e32 v14, v0
	v_mov_b32_e32 v15, v0
	v_mov_b32_e32 v4, v0
	v_mov_b32_e32 v5, v0
	v_mov_b32_e32 v6, v0
	v_mov_b32_e32 v7, v0
	v_lshl_add_u64 v[106:107], v[16:17], 0, s[18:19]
	global_load_dwordx4 v[106:109], v[106:107], off offset:0
	v_lshl_add_u64 v[110:111], v[18:19], 0, s[18:19]
	global_load_dwordx4 v[110:113], v[110:111], off offset:0
	v_lshl_add_u64 v[114:115], v[20:21], 0, s[18:19]
	global_load_dwordx4 v[114:117], v[114:115], off offset:0
	v_lshl_add_u64 v[118:119], v[22:23], 0, s[18:19]
	global_load_dwordx4 v[118:121], v[118:119], off offset:0
	v_lshl_add_u64 v[122:123], v[24:25], 0, s[18:19]
	global_load_dwordx4 v[122:125], v[122:123], off offset:0
	v_lshl_add_u64 v[126:127], v[16:17], 0, s[18:19]
	global_load_dwordx4 v[126:129], v[126:127], off offset:64
	v_lshl_add_u64 v[130:131], v[18:19], 0, s[18:19]
	global_load_dwordx4 v[130:133], v[130:131], off offset:64
	v_lshl_add_u64 v[134:135], v[20:21], 0, s[18:19]
	global_load_dwordx4 v[134:137], v[134:135], off offset:64
	v_lshl_add_u64 v[138:139], v[22:23], 0, s[18:19]
	global_load_dwordx4 v[138:141], v[138:139], off offset:64
	v_lshl_add_u64 v[142:143], v[24:25], 0, s[18:19]
	global_load_dwordx4 v[142:145], v[142:143], off offset:64
	v_lshl_add_u64 v[26:27], v[16:17], 0, s[18:19]
	global_load_dwordx4 v[26:29], v[26:27], off offset:128
	v_lshl_add_u64 v[30:31], v[18:19], 0, s[18:19]
	global_load_dwordx4 v[30:33], v[30:31], off offset:128
	v_lshl_add_u64 v[34:35], v[20:21], 0, s[18:19]
	global_load_dwordx4 v[34:37], v[34:35], off offset:128
	v_lshl_add_u64 v[38:39], v[22:23], 0, s[18:19]
	global_load_dwordx4 v[38:41], v[38:39], off offset:128
	s_waitcnt vmcnt(12)
	v_mfma_f32_16x16x32_bf16 v[8:11], v[110:113], v[106:109], v[8:11]
	v_lshl_add_u64 v[110:111], v[24:25], 0, s[18:19]
	global_load_dwordx4 v[110:113], v[110:111], off offset:128
	s_waitcnt vmcnt(12)
	v_mfma_f32_16x16x32_bf16 v[12:15], v[114:117], v[106:109], v[12:15]
	v_lshl_add_u64 v[114:115], v[16:17], 0, s[18:19]
	global_load_dwordx4 v[114:117], v[114:115], off offset:192
	s_waitcnt vmcnt(12)
	v_mfma_f32_16x16x32_bf16 v[4:7], v[118:121], v[106:109], v[4:7]
	v_lshl_add_u64 v[118:119], v[18:19], 0, s[18:19]
	global_load_dwordx4 v[118:121], v[118:119], off offset:192
	s_waitcnt vmcnt(12)
	v_mfma_f32_16x16x32_bf16 v[0:3], v[122:125], v[106:109], v[0:3]
	v_lshl_add_u64 v[122:123], v[20:21], 0, s[18:19]
	global_load_dwordx4 v[122:125], v[122:123], off offset:192
	v_lshl_add_u64 v[106:107], v[22:23], 0, s[18:19]
	global_load_dwordx4 v[106:109], v[106:107], off offset:192
	s_waitcnt vmcnt(12)
	v_mfma_f32_16x16x32_bf16 v[8:11], v[130:133], v[126:129], v[8:11]
	v_lshl_add_u64 v[130:131], v[24:25], 0, s[18:19]
	global_load_dwordx4 v[130:133], v[130:131], off offset:192
	s_waitcnt vmcnt(12)
	v_mfma_f32_16x16x32_bf16 v[12:15], v[134:137], v[126:129], v[12:15]
	s_waitcnt vmcnt(11)
	v_mfma_f32_16x16x32_bf16 v[4:7], v[138:141], v[126:129], v[4:7]
	s_waitcnt vmcnt(10)
	v_mfma_f32_16x16x32_bf16 v[0:3], v[142:145], v[126:129], v[0:3]
	s_waitcnt vmcnt(8)
	v_mfma_f32_16x16x32_bf16 v[8:11], v[30:33], v[26:29], v[8:11]
	s_waitcnt vmcnt(7)
	v_mfma_f32_16x16x32_bf16 v[12:15], v[34:37], v[26:29], v[12:15]
	s_waitcnt vmcnt(6)
	v_mfma_f32_16x16x32_bf16 v[4:7], v[38:41], v[26:29], v[4:7]
	s_waitcnt vmcnt(5)
	v_mfma_f32_16x16x32_bf16 v[0:3], v[110:113], v[26:29], v[0:3]
	s_waitcnt vmcnt(3)
	v_mfma_f32_16x16x32_bf16 v[8:11], v[118:121], v[114:117], v[8:11]
	s_waitcnt vmcnt(2)
	v_mfma_f32_16x16x32_bf16 v[12:15], v[122:125], v[114:117], v[12:15]
	s_waitcnt vmcnt(1)
	v_mfma_f32_16x16x32_bf16 v[4:7], v[106:109], v[114:117], v[4:7]
	s_waitcnt vmcnt(0)
	v_mfma_f32_16x16x32_bf16 v[0:3], v[130:133], v[114:117], v[0:3]
	v_add_u32_e32 v16, s2, v91
	s_and_b64 vcc, exec, s[0:1]
	ds_write_b128 v16, v[8:11]
	ds_write_b128 v16, v[12:15] offset:1024
	s_nop 0
	ds_write_b128 v16, v[4:7] offset:2048
	s_nop 0
	ds_write_b128 v16, v[0:3] offset:3072
	s_waitcnt lgkmcnt(0)
	s_barrier
	s_cbranch_vccz .LBB0_375
; #define GAS __attribute__((address_space(1)))
; __device__ __forceinline__ float row_rstd(const GAS float* ssp, int row) {
;     const GAS f32x4* p = (const GAS f32x4*)(ssp + (size_t)row * 16);
;     const f32x4 a = p[0], b = p[1], c = p[2], d = p[3];
;     const float s = ((a[0] + a[1]) + (a[2] + a[3])) + ((b[0] + b[1]) + (b[2] + b[3])) + ((c[0] + c[1]) + (c[2] + c[3])) + ((d[0] + d[1]) + (d[2] + d[3]));
;     return rsqrtf(s * (1.0f / 1024.0f) + EPS);
; }
; template <int MODE, bool SMALL>
; __device__ __forceinline__ float epi_apply(const EpiArgs& a, int row, int g32, int fq, f32x4 v0, f32x4 v1, float rstd) {
;     const int c0 = 32 * g32 + 8 * fq;
;     if constexpr (MODE == 0) {
;         if (g32 >= ABIN / 32) return 0.f;
;         v0 *= rstd; v1 *= rstd;
;         u32x4 w; w.x = pk2(v0[0], v0[1]); w.y = pk2(v0[2], v0[3]); w.z = pk2(v1[0], v1[1]); w.w = pk2(v1[2], v1[3]);
;         *(GAS u32x4*)(a.out + (size_t)row * ABIN + c0) = w;
;         if (g32 == 48 && fq < 2) { GAS float* gp = a.gates + (size_t)row * 32 + 8 * fq; *(GAS f32x4*)gp = v0; *(GAS f32x4*)(gp + 4) = v1; }
;         if (g32 == 96 && fq >= 2) { GAS float* gp = a.gates + (size_t)row * 32 + 16 + 8 * (fq - 2); *(GAS f32x4*)gp = v0; *(GAS f32x4*)(gp + 4) = v1; }
;         if (c0 < DNQKV) {
;             if constexpr (!SMALL) { const int t = row & (SEQ - 1), b = row >> 12; if (t >= SEQ - 3) { GAS float* d = a.o0 + (size_t)(b * 3 + (t - (SEQ - 3))) * DNQKV + c0; *(GAS f32x4*)d = v0; *(GAS f32x4*)(d + 4) = v1; } }
; template <int MODE>
; __device__ __forceinline__ void small_gemm(const bf16_t* A, const bf16_t* Bt, int Npos, int K, const LAS unsigned long long* eap, LAS unsigned char* lds, int wg, int G, int wid, int lane) {
;     ...
;         if (wid == 0) {
; #pragma unroll
;             for (int w = 1; w < 8; ++w)
; #pragma unroll
;                 for (int f = 0; f < 4; ++f) acc[f] += part[(w * 4 + f) * 64 + lane];
;             const int row = r0 + fr;
;             const EpiArgs a = load_ea(eap);
;             float rstd = 1.f; if constexpr (MODE != 2) rstd = row_rstd(a.ssp, row);
;             float ss = 0.f;
; #pragma unroll
;             for (int gq = 0; gq < 2; ++gq) ss += epi_apply<MODE, true>(a, row, (p0 >> 5) + gq, fq, acc[2 * gq], acc[2 * gq + 1], rstd);
	ds_read_b128 v[16:19], v91 offset:4096
	v_readlane_b32 s14, v245, 2
	s_waitcnt lgkmcnt(0)
	v_pk_add_f32 v[18:19], v[10:11], v[18:19]
	v_pk_add_f32 v[16:17], v[8:9], v[16:17]
	ds_read_b128 v[8:11], v91 offset:5120
	s_waitcnt lgkmcnt(0)
	v_pk_add_f32 v[20:21], v[14:15], v[10:11]
	v_pk_add_f32 v[22:23], v[12:13], v[8:9]
	ds_read_b128 v[60:63], v91 offset:6144
	ds_read_b128 v[8:11], v91 offset:7168
	ds_read_b128 v[12:15], v91 offset:8192
	s_waitcnt lgkmcnt(0)
	v_pk_add_f32 v[24:25], v[18:19], v[14:15]
	v_pk_add_f32 v[26:27], v[16:17], v[12:13]
	ds_read_b128 v[12:15], v91 offset:9216
	s_waitcnt lgkmcnt(0)
	v_pk_add_f32 v[20:21], v[20:21], v[14:15]
	v_pk_add_f32 v[22:23], v[22:23], v[12:13]
	ds_read_b128 v[36:39], v91 offset:10240
	ds_read_b128 v[12:15], v91 offset:11264
	ds_read_b128 v[16:19], v91 offset:12288
	s_waitcnt lgkmcnt(0)
	v_pk_add_f32 v[24:25], v[24:25], v[18:19]
	v_pk_add_f32 v[26:27], v[26:27], v[16:17]
	ds_read_b128 v[16:19], v91 offset:13312
	s_waitcnt lgkmcnt(0)
	v_pk_add_f32 v[28:29], v[20:21], v[18:19]
	v_pk_add_f32 v[30:31], v[22:23], v[16:17]
	ds_read_b128 v[40:43], v91 offset:14336
	ds_read_b128 v[16:19], v91 offset:15360
	ds_read_b128 v[20:23], v91 offset:16384
	s_waitcnt lgkmcnt(0)
	v_pk_add_f32 v[32:33], v[24:25], v[22:23]
	v_pk_add_f32 v[34:35], v[26:27], v[20:21]
	ds_read_b128 v[20:23], v91 offset:17408
	s_waitcnt lgkmcnt(0)
	v_pk_add_f32 v[28:29], v[28:29], v[22:23]
	v_pk_add_f32 v[30:31], v[30:31], v[20:21]
	ds_read_b128 v[44:47], v91 offset:18432
	ds_read_b128 v[20:23], v91 offset:19456
	ds_read_b128 v[24:27], v91 offset:20480
	s_waitcnt lgkmcnt(0)
	v_pk_add_f32 v[32:33], v[32:33], v[26:27]
	v_pk_add_f32 v[34:35], v[34:35], v[24:25]
	ds_read_b128 v[24:27], v91 offset:21504
	s_waitcnt lgkmcnt(0)
	v_pk_add_f32 v[52:53], v[28:29], v[26:27]
	v_pk_add_f32 v[54:55], v[30:31], v[24:25]
	ds_read_b128 v[48:51], v91 offset:22528
	ds_read_b128 v[24:27], v91 offset:23552
	ds_read_b128 v[28:31], v91 offset:24576
	s_waitcnt lgkmcnt(0)
	v_pk_add_f32 v[56:57], v[32:33], v[30:31]
	v_pk_add_f32 v[58:59], v[34:35], v[28:29]
	ds_read_b128 v[28:31], v91 offset:25600
	s_waitcnt lgkmcnt(0)
	v_pk_add_f32 v[64:65], v[52:53], v[30:31]
	v_pk_add_f32 v[66:67], v[54:55], v[28:29]
	ds_read_b128 v[52:55], v91 offset:26624
	ds_read_b128 v[28:31], v91 offset:27648
	ds_read_b128 v[32:35], v91 offset:28672
	s_waitcnt lgkmcnt(0)
	v_pk_add_f32 v[68:69], v[56:57], v[34:35]
	v_pk_add_f32 v[70:71], v[58:59], v[32:33]
	ds_read_b128 v[32:35], v91 offset:29696
	s_waitcnt lgkmcnt(0)
	v_pk_add_f32 v[78:79], v[64:65], v[34:35]
	v_mov_b32_e32 v64, s14
	v_pk_add_f32 v[80:81], v[66:67], v[32:33]
	ds_read_b128 v[56:59], v91 offset:30720
	ds_read_b128 v[32:35], v91 offset:31744
	ds_read_b128 v[64:67], v64
	v_readlane_b32 s14, v245, 8
	s_nop 1
	v_mov_b32_e32 v82, s14
	ds_read_b64 v[84:85], v82
	v_lshlrev_b64 v[82:83], 6, v[160:161]
	s_waitcnt lgkmcnt(1)
	v_lshl_add_u64 v[66:67], v[66:67], 0, v[82:83]
	global_load_dwordx4 v[86:89], v[66:67], off offset:48
	global_load_dwordx4 v[94:97], v[66:67], off offset:32
	global_load_dwordx4 v[98:101], v[66:67], off offset:16
	global_load_dwordx4 v[102:105], v[66:67], off
	s_movk_i32 s14, 0xc00
	s_waitcnt vmcnt(2)
	v_add_f32_e32 v94, v94, v95
	s_waitcnt vmcnt(1)
	v_mov_b32_e32 v82, v99
	s_waitcnt vmcnt(0)
	v_mov_b32_e32 v66, v103
	v_mov_b32_e32 v67, v104
	v_mov_b32_e32 v103, v105
	v_mov_b32_e32 v83, v100
	v_mov_b32_e32 v99, v101
	v_pk_add_f32 v[66:67], v[66:67], v[102:103]
	v_pk_add_f32 v[82:83], v[82:83], v[98:99]
	v_pk_add_f32 v[66:67], v[66:67], v[66:67] op_sel:[0,1] op_sel_hi:[1,0]
	v_pk_add_f32 v[82:83], v[82:83], v[82:83] op_sel:[0,1] op_sel_hi:[1,0]
	v_add_f32_e32 v96, v96, v97
	v_mov_b32_e32 v67, v86
	v_mov_b32_e32 v83, v87
	v_mov_b32_e32 v95, v88
	v_mov_b32_e32 v97, v89
	v_pk_add_f32 v[66:67], v[66:67], v[82:83]
	v_pk_add_f32 v[82:83], v[94:95], v[96:97]
	v_or_b32_e32 v86, s13, v92
	v_pk_add_f32 v[66:67], v[66:67], v[82:83]
	v_ashrrev_i32_e32 v87, 31, v86
	v_add_f32_e32 v66, v66, v67
	v_fmamk_f32 v66, v66, 0x3a800000, v162
	v_cmp_gt_f32_e32 vcc, s3, v66
	v_mul_f32_e32 v67, 0x4b800000, v66
	s_nop 0
	v_cndmask_b32_e32 v66, v66, v67, vcc
	v_rsq_f32_e32 v66, v66
	s_nop 0
	v_mul_f32_e32 v67, 0x45800000, v66
	v_cndmask_b32_e32 v82, v66, v67, vcc
	v_mul_lo_u32 v66, v160, s14
	v_mov_b32_e32 v67, v161
	v_lshl_add_u64 v[88:89], v[66:67], 1, v[64:65]
	v_ashrrev_i32_e32 v65, 31, v160
	v_mov_b32_e32 v64, v160
	v_lshlrev_b64 v[64:65], 12, v[64:65]
	s_brev_b32 s14, 31
	s_waitcnt lgkmcnt(0)
	v_lshl_add_u64 v[64:65], v[84:85], 0, v[64:65]
	s_mov_b32 s15, -1
	v_lshl_add_u64 v[84:85], v[64:65], 0, s[14:15]
	v_pk_mul_f32 v[66:67], v[68:69], v[82:83] op_sel_hi:[1,0]
	v_pk_mul_f32 v[64:65], v[70:71], v[82:83] op_sel_hi:[1,0]
	v_pk_mul_f32 v[70:71], v[78:79], v[82:83] op_sel_hi:[1,0]
	v_pk_mul_f32 v[68:69], v[80:81], v[82:83] op_sel_hi:[1,0]
	v_cvt_pk_bf16_f32 v94, v64, v65
	v_cvt_pk_bf16_f32 v95, v66, v67
	v_cvt_pk_bf16_f32 v96, v68, v69
	v_cvt_pk_bf16_f32 v97, v70, v71
	v_lshl_add_u64 v[78:79], v[86:87], 1, v[88:89]
	v_cmp_lt_i32_e32 vcc, s17, v86
	global_store_dwordx4 v[78:79], v[94:97], off
	s_and_saveexec_b64 s[28:29], vcc
	s_cbranch_execz .LBB0_381
	s_cmpk_gt_u32 s13, 0x7ff
	s_cselect_b64 s[14:15], -1, 0
	s_and_b64 s[14:15], s[14:15], exec
	s_cselect_b32 s14, 0xfffffc00, 0
	s_cselect_b32 s36, 0x2100000, 0
	v_add_u32_e32 v83, s14, v86
	v_lshl_add_u64 v[80:81], v[84:85], 0, s[36:37]
	v_add_u32_e32 v160, 0xfffffc00, v83
	v_lshl_add_u64 v[80:81], v[160:161], 2, v[80:81]
	global_store_dwordx4 v[80:81], v[64:67], off
	global_store_dwordx4 v[80:81], v[68:71], off offset:16

; template <int MODE>
; __device__ __forceinline__ void small_gemm(const bf16_t* A, const bf16_t* Bt, int Npos, int K, const LAS unsigned long long* eap, LAS unsigned char* lds, int wg, int G, int wid, int lane) {
;     ...
;         const int rb = u % (TS / 16), cgp = u / (TS / 16), r0 = TP + rb * 16, p0 = cgp * 64;
;         f32x4 acc[4];
; #pragma unroll
;         for (int f = 0; f < 4; ++f) acc[f] = (f32x4){0.f, 0.f, 0.f, 0.f};
;         const bf16_t* ap = A + (size_t)(r0 + fr) * K + wid * KW + 8 * fq;
;         const bf16_t* bp = Bt + (size_t)(p0 + fr) * K + wid * KW + 8 * fq;
;         for (int k0 = 0; k0 < KW; k0 += 32) {
;             const bf16x8 av = *(const bf16x8*)(ap + k0);
;             bf16x8 wv[4];
; #pragma unroll
;             for (int f = 0; f < 4; ++f) wv[f] = *(const bf16x8*)(bp + (size_t)(16 * f) * K + k0);
; #pragma unroll
;             for (int f = 0; f < 4; ++f) acc[f] = __builtin_amdgcn_mfma_f32_16x16x32_bf16(wv[f], av, acc[f], 0, 0, 0);
;         }
; #pragma unroll
;         for (int f = 0; f < 4; ++f) part[(wid * 4 + f) * 64 + lane] = acc[f];
;         __syncthreads();
.LBB0_445:
	s_ashr_i32 s14, s13, 31
	s_lshr_b32 s14, s14, 29
	s_add_i32 s15, s13, s14
	s_and_b32 s14, s15, -8
	s_lshl_b32 s15, s15, 3
	s_andn2_b32 s15, s15, 63
	v_or_b32_e32 v0, s15, v165
	v_lshlrev_b32_e32 v2, 1, v0
	s_sub_i32 s14, s13, s14
	v_or_b32_e32 v3, 32, v2
	v_or_b32_e32 v2, 64, v2
	v_lshl_add_u32 v160, s14, 4, v79
	v_ashrrev_i32_e32 v1, 31, v0
	v_mad_i64_i32 v[10:11], s[22:23], s12, v0, v[82:83]
	v_mad_u64_u32 v[12:13], s[22:23], s48, v3, v[82:83]
	v_mad_u64_u32 v[14:15], s[22:23], s48, v2, v[82:83]
	v_mad_i64_i32 v[16:17], s[22:23], s12, v0, v[84:85]
	v_mov_b32_e32 v0, 0
	v_mad_u64_u32 v[8:9], s[22:23], s12, v160, v[80:81]
	v_mad_i32_i24 v13, s48, v1, v13
	v_mad_i32_i24 v15, s48, v1, v15
	s_mov_b32 s17, 0
	v_mov_b32_e32 v1, v0
	v_mov_b32_e32 v2, v0
	v_mov_b32_e32 v3, v0
	v_mov_b32_e32 v64, v0
	v_mov_b32_e32 v65, v0
	v_mov_b32_e32 v66, v0
	v_mov_b32_e32 v67, v0
	v_mov_b32_e32 v68, v0
	v_mov_b32_e32 v69, v0
	v_mov_b32_e32 v70, v0
	v_mov_b32_e32 v71, v0
	v_mov_b32_e32 v4, v0
	v_mov_b32_e32 v5, v0
	v_mov_b32_e32 v6, v0
	v_mov_b32_e32 v7, v0
	v_lshl_add_u64 v[108:109], v[8:9], 0, s[18:19]
	global_load_dwordx4 v[108:111], v[108:109], off offset:0
	v_lshl_add_u64 v[112:113], v[10:11], 0, s[18:19]
	global_load_dwordx4 v[112:115], v[112:113], off offset:0
	v_lshl_add_u64 v[116:117], v[12:13], 0, s[18:19]
	global_load_dwordx4 v[116:119], v[116:117], off offset:0
	v_lshl_add_u64 v[120:121], v[14:15], 0, s[18:19]
	global_load_dwordx4 v[120:123], v[120:121], off offset:0
	v_lshl_add_u64 v[124:125], v[16:17], 0, s[18:19]
	global_load_dwordx4 v[124:127], v[124:125], off offset:0
	v_lshl_add_u64 v[128:129], v[8:9], 0, s[18:19]
	global_load_dwordx4 v[128:131], v[128:129], off offset:64
	v_lshl_add_u64 v[132:133], v[10:11], 0, s[18:19]
	global_load_dwordx4 v[132:135], v[132:133], off offset:64
	v_lshl_add_u64 v[136:137], v[12:13], 0, s[18:19]
	global_load_dwordx4 v[136:139], v[136:137], off offset:64
	v_lshl_add_u64 v[140:141], v[14:15], 0, s[18:19]
	global_load_dwordx4 v[140:143], v[140:141], off offset:64
	v_lshl_add_u64 v[144:145], v[16:17], 0, s[18:19]
	global_load_dwordx4 v[144:147], v[144:145], off offset:64
	v_lshl_add_u64 v[148:149], v[8:9], 0, s[18:19]
	global_load_dwordx4 v[148:151], v[148:149], off offset:128
	v_lshl_add_u64 v[18:19], v[10:11], 0, s[18:19]
	global_load_dwordx4 v[18:21], v[18:19], off offset:128
	v_lshl_add_u64 v[22:23], v[12:13], 0, s[18:19]
	global_load_dwordx4 v[22:25], v[22:23], off offset:128
	v_lshl_add_u64 v[26:27], v[14:15], 0, s[18:19]
	global_load_dwordx4 v[26:29], v[26:27], off offset:128
	v_lshl_add_u64 v[30:31], v[16:17], 0, s[18:19]
	global_load_dwordx4 v[30:33], v[30:31], off offset:128
	s_waitcnt vmcnt(13)
	v_mfma_f32_16x16x32_bf16 v[64:67], v[112:115], v[108:111], v[64:67]
	v_lshl_add_u64 v[112:113], v[8:9], 0, s[18:19]
	global_load_dwordx4 v[112:115], v[112:113], off offset:192
	s_waitcnt vmcnt(13)
	v_mfma_f32_16x16x32_bf16 v[68:71], v[116:119], v[108:111], v[68:71]
	v_lshl_add_u64 v[116:117], v[10:11], 0, s[18:19]
	global_load_dwordx4 v[116:119], v[116:117], off offset:192
	s_waitcnt vmcnt(13)
	v_mfma_f32_16x16x32_bf16 v[4:7], v[120:123], v[108:111], v[4:7]
	v_lshl_add_u64 v[120:121], v[12:13], 0, s[18:19]
	global_load_dwordx4 v[120:123], v[120:121], off offset:192
	s_waitcnt vmcnt(13)
	v_mfma_f32_16x16x32_bf16 v[0:3], v[124:127], v[108:111], v[0:3]
	v_lshl_add_u64 v[124:125], v[14:15], 0, s[18:19]
	global_load_dwordx4 v[124:127], v[124:125], off offset:192
	v_lshl_add_u64 v[108:109], v[16:17], 0, s[18:19]
	global_load_dwordx4 v[108:111], v[108:109], off offset:192
	s_waitcnt vmcnt(13)
	v_mfma_f32_16x16x32_bf16 v[64:67], v[132:135], v[128:131], v[64:67]
	s_waitcnt vmcnt(12)
	v_mfma_f32_16x16x32_bf16 v[68:71], v[136:139], v[128:131], v[68:71]
	s_waitcnt vmcnt(11)
	v_mfma_f32_16x16x32_bf16 v[4:7], v[140:143], v[128:131], v[4:7]
	s_waitcnt vmcnt(10)
	v_mfma_f32_16x16x32_bf16 v[0:3], v[144:147], v[128:131], v[0:3]
	s_waitcnt vmcnt(8)
	v_mfma_f32_16x16x32_bf16 v[64:67], v[18:21], v[148:151], v[64:67]
	s_waitcnt vmcnt(7)
	v_mfma_f32_16x16x32_bf16 v[68:71], v[22:25], v[148:151], v[68:71]
	s_waitcnt vmcnt(6)
	v_mfma_f32_16x16x32_bf16 v[4:7], v[26:29], v[148:151], v[4:7]
	s_waitcnt vmcnt(5)
	v_mfma_f32_16x16x32_bf16 v[0:3], v[30:33], v[148:151], v[0:3]
	s_waitcnt vmcnt(3)
	v_mfma_f32_16x16x32_bf16 v[64:67], v[116:119], v[112:115], v[64:67]
	s_waitcnt vmcnt(2)
	v_mfma_f32_16x16x32_bf16 v[68:71], v[120:123], v[112:115], v[68:71]
	s_waitcnt vmcnt(1)
	v_mfma_f32_16x16x32_bf16 v[4:7], v[124:127], v[112:115], v[4:7]
	s_waitcnt vmcnt(0)
	v_mfma_f32_16x16x32_bf16 v[0:3], v[108:111], v[112:115], v[0:3]
	v_add_u32_e32 v8, s4, v94
	s_and_b64 vcc, exec, s[0:1]
	ds_write_b128 v8, v[64:67]
	ds_write_b128 v8, v[68:71] offset:1024
	s_nop 0
	ds_write_b128 v8, v[4:7] offset:2048
	s_nop 0
	ds_write_b128 v8, v[0:3] offset:3072
	s_waitcnt lgkmcnt(0)
	s_barrier
	s_cbranch_vccz .LBB0_444
; #define GAS __attribute__((address_space(1)))
; __device__ __forceinline__ float row_rstd(const GAS float* ssp, int row) {
;     const GAS f32x4* p = (const GAS f32x4*)(ssp + (size_t)row * 16);
;     const f32x4 a = p[0], b = p[1], c = p[2], d = p[3];
;     const float s = ((a[0] + a[1]) + (a[2] + a[3])) + ((b[0] + b[1]) + (b[2] + b[3])) + ((c[0] + c[1]) + (c[2] + c[3])) + ((d[0] + d[1]) + (d[2] + d[3]));
;     return rsqrtf(s * (1.0f / 1024.0f) + EPS);
; }
; template <int MODE, bool SMALL>
; __device__ __forceinline__ float epi_apply(const EpiArgs& a, int row, int g32, int fq, f32x4 v0, f32x4 v1, float rstd) {
;     const int c0 = 32 * g32 + 8 * fq;
;     if constexpr (MODE == 0) {
;         if (g32 >= ABIN / 32) return 0.f;
;         v0 *= rstd; v1 *= rstd;
;         u32x4 w; w.x = pk2(v0[0], v0[1]); w.y = pk2(v0[2], v0[3]); w.z = pk2(v1[0], v1[1]); w.w = pk2(v1[2], v1[3]);
;         *(GAS u32x4*)(a.out + (size_t)row * ABIN + c0) = w;
;         if (g32 == 48 && fq < 2) { GAS float* gp = a.gates + (size_t)row * 32 + 8 * fq; *(GAS f32x4*)gp = v0; *(GAS f32x4*)(gp + 4) = v1; }
;         if (g32 == 96 && fq >= 2) { GAS float* gp = a.gates + (size_t)row * 32 + 16 + 8 * (fq - 2); *(GAS f32x4*)gp = v0; *(GAS f32x4*)(gp + 4) = v1; }
;         if (c0 < DNQKV) {
;             if constexpr (!SMALL) { const int t = row & (SEQ - 1), b = row >> 12; if (t >= SEQ - 3) { GAS float* d = a.o0 + (size_t)(b * 3 + (t - (SEQ - 3))) * DNQKV + c0; *(GAS f32x4*)d = v0; *(GAS f32x4*)(d + 4) = v1; } }
; template <int MODE>
; __device__ __forceinline__ void small_gemm(const bf16_t* A, const bf16_t* Bt, int Npos, int K, const LAS unsigned long long* eap, LAS unsigned char* lds, int wg, int G, int wid, int lane) {
;     ...
;         if (wid == 0) {
; #pragma unroll
;             for (int w = 1; w < 8; ++w)
; #pragma unroll
;                 for (int f = 0; f < 4; ++f) acc[f] += part[(w * 4 + f) * 64 + lane];
;             const int row = r0 + fr;
;             const EpiArgs a = load_ea(eap);
;             float rstd = 1.f; if constexpr (MODE != 2) rstd = row_rstd(a.ssp, row);
;             float ss = 0.f;
; #pragma unroll
;             for (int gq = 0; gq < 2; ++gq) ss += epi_apply<MODE, true>(a, row, (p0 >> 5) + gq, fq, acc[2 * gq], acc[2 * gq + 1], rstd);
	v_readlane_b32 s17, v245, 2
	ds_read_b128 v[60:63], v94 offset:6144
	ds_read_b128 v[56:59], v94 offset:7168
	ds_read_b128 v[52:55], v94 offset:10240
	ds_read_b128 v[48:51], v94 offset:11264
	ds_read_b128 v[44:47], v94 offset:14336
	ds_read_b128 v[40:43], v94 offset:15360
	ds_read_b128 v[36:39], v94 offset:18432
	ds_read_b128 v[32:35], v94 offset:19456
	ds_read_b128 v[28:31], v94 offset:22528
	ds_read_b128 v[24:27], v94 offset:23552
	ds_read_b128 v[20:23], v94 offset:26624
	ds_read_b128 v[16:19], v94 offset:27648
	ds_read_b128 v[12:15], v94 offset:30720
	ds_read_b128 v[8:11], v94 offset:31744
	v_mov_b32_e32 v72, s17
	ds_read_b128 v[72:75], v72
	v_readlane_b32 s17, v245, 9
	v_lshlrev_b64 v[90:91], 6, v[160:161]
	s_nop 0
	v_mov_b32_e32 v86, s17
	ds_read_b64 v[88:89], v86
	v_mov_b32_e32 v86, s25
	s_waitcnt lgkmcnt(1)
	v_lshl_add_u64 v[74:75], v[74:75], 0, v[90:91]
	ds_read_b64 v[86:87], v86
	global_load_dwordx4 v[90:93], v[74:75], off offset:48
	global_load_dwordx4 v[96:99], v[74:75], off offset:32
	global_load_dwordx4 v[100:103], v[74:75], off offset:16
	global_load_dwordx4 v[104:107], v[74:75], off
	s_waitcnt vmcnt(2)
	v_add_f32_e32 v96, v96, v97
	v_add_f32_e32 v98, v98, v99
	s_waitcnt vmcnt(0)
	v_mov_b32_e32 v74, v105
	v_mov_b32_e32 v75, v106
	v_mov_b32_e32 v105, v107
	v_pk_add_f32 v[74:75], v[74:75], v[104:105]
	v_mov_b32_e32 v104, v101
	v_mov_b32_e32 v105, v102
	v_mov_b32_e32 v101, v103
	v_pk_add_f32 v[100:101], v[104:105], v[100:101]
	v_pk_add_f32 v[74:75], v[74:75], v[74:75] op_sel:[0,1] op_sel_hi:[1,0]
	v_pk_add_f32 v[100:101], v[100:101], v[100:101] op_sel:[0,1] op_sel_hi:[1,0]
	v_mov_b32_e32 v97, v92
	v_mov_b32_e32 v99, v93
	v_mov_b32_e32 v75, v90
	v_mov_b32_e32 v101, v91
	v_pk_add_f32 v[90:91], v[96:97], v[98:99]
	ds_read_b128 v[96:99], v94 offset:5120
	v_pk_add_f32 v[74:75], v[74:75], v[100:101]
	s_waitcnt lgkmcnt(0)
	v_pk_add_f32 v[92:93], v[70:71], v[98:99]
	v_pk_add_f32 v[96:97], v[68:69], v[96:97]
	ds_read_b128 v[68:71], v94 offset:9216
	v_pk_add_f32 v[74:75], v[74:75], v[90:91]
	v_lshlrev_b32_e32 v90, 2, v76
	v_add_f32_e32 v74, v74, v75
	v_fmamk_f32 v74, v74, 0x3a800000, v162
	s_waitcnt lgkmcnt(0)
	v_pk_add_f32 v[92:93], v[92:93], v[70:71]
	v_pk_add_f32 v[96:97], v[96:97], v[68:69]
	ds_read_b128 v[68:71], v94 offset:13312
	v_cmp_gt_f32_e32 vcc, s3, v74
	v_mul_f32_e32 v75, 0x4b800000, v74
	v_mov_b32_e32 v91, v161
	v_cndmask_b32_e32 v74, v74, v75, vcc
	s_waitcnt lgkmcnt(0)
	v_pk_add_f32 v[92:93], v[92:93], v[70:71]
	v_pk_add_f32 v[96:97], v[96:97], v[68:69]
	ds_read_b128 v[68:71], v94 offset:17408
	v_rsq_f32_e32 v74, v74
	v_lshl_add_u64 v[88:89], v[88:89], 0, v[90:91]
	v_mad_u64_u32 v[90:91], s[22:23], v160, s5, v[72:73]
	s_waitcnt lgkmcnt(0)
	v_pk_add_f32 v[92:93], v[92:93], v[70:71]
	v_pk_add_f32 v[96:97], v[96:97], v[68:69]
	ds_read_b128 v[68:71], v94 offset:21504
	v_lshlrev_b64 v[72:73], 7, v[160:161]
	v_mul_f32_e32 v75, 0x45800000, v74
	v_lshl_add_u64 v[88:89], v[88:89], 0, v[72:73]
	v_or_b32_e32 v72, s15, v76
	s_waitcnt lgkmcnt(0)
	v_pk_add_f32 v[92:93], v[92:93], v[70:71]
	v_pk_add_f32 v[96:97], v[96:97], v[68:69]
	ds_read_b128 v[68:71], v94 offset:25600
	s_and_b32 s15, s13, -8
	v_cndmask_b32_e32 v74, v74, v75, vcc
	s_cmpk_eq_i32 s15, 0xc0
	v_ashrrev_i32_e32 v73, 31, v72
	s_waitcnt lgkmcnt(0)
	v_pk_add_f32 v[70:71], v[92:93], v[70:71]
	v_pk_add_f32 v[92:93], v[96:97], v[68:69]
	ds_read_b128 v[96:99], v94 offset:29696
	s_cselect_b64 s[22:23], -1, 0
	v_lshl_add_u64 v[90:91], v[72:73], 1, v[90:91]
	s_and_b64 s[22:23], s[22:23], s[38:39]
	s_waitcnt lgkmcnt(0)
	v_pk_add_f32 v[68:69], v[70:71], v[98:99]
	v_pk_add_f32 v[92:93], v[92:93], v[96:97]
	ds_read_b128 v[96:99], v94 offset:4096
	s_waitcnt lgkmcnt(0)
	v_pk_add_f32 v[70:71], v[66:67], v[98:99]
	v_pk_add_f32 v[96:97], v[64:65], v[96:97]
	ds_read_b128 v[64:67], v94 offset:8192
	s_waitcnt lgkmcnt(0)
	v_pk_add_f32 v[70:71], v[70:71], v[66:67]
	v_pk_add_f32 v[96:97], v[96:97], v[64:65]
	ds_read_b128 v[64:67], v94 offset:12288
	s_waitcnt lgkmcnt(0)
	v_pk_add_f32 v[70:71], v[70:71], v[66:67]
	v_pk_add_f32 v[96:97], v[96:97], v[64:65]
	ds_read_b128 v[64:67], v94 offset:16384
	s_waitcnt lgkmcnt(0)
	v_pk_add_f32 v[70:71], v[70:71], v[66:67]
	v_pk_add_f32 v[96:97], v[96:97], v[64:65]
	ds_read_b128 v[64:67], v94 offset:20480
	s_waitcnt lgkmcnt(0)
	v_pk_add_f32 v[70:71], v[70:71], v[66:67]
	v_pk_add_f32 v[96:97], v[96:97], v[64:65]
	ds_read_b128 v[64:67], v94 offset:24576
	s_waitcnt lgkmcnt(0)
	v_pk_add_f32 v[70:71], v[70:71], v[66:67]
	v_pk_add_f32 v[96:97], v[96:97], v[64:65]
	ds_read_b128 v[64:67], v94 offset:28672
	s_waitcnt lgkmcnt(0)
	v_pk_add_f32 v[66:67], v[70:71], v[66:67]
	v_pk_add_f32 v[64:65], v[96:97], v[64:65]
	v_pk_mul_f32 v[66:67], v[74:75], v[66:67] op_sel_hi:[0,1]
	v_pk_mul_f32 v[64:65], v[74:75], v[64:65] op_sel_hi:[0,1]
	v_pk_mul_f32 v[70:71], v[68:69], v[74:75] op_sel_hi:[1,0]
	v_pk_mul_f32 v[68:69], v[92:93], v[74:75] op_sel_hi:[1,0]
	v_cvt_pk_bf16_f32 v96, v64, v65
	v_cvt_pk_bf16_f32 v97, v66, v67
	v_cvt_pk_bf16_f32 v98, v68, v69
	v_cvt_pk_bf16_f32 v99, v70, v71
	global_store_dwordx4 v[90:91], v[96:99], off
	s_and_saveexec_b64 s[28:29], s[22:23]
	s_cbranch_execz .LBB0_450
	global_store_dwordx4 v[88:89], v[64:67], off
	global_store_dwordx4 v[88:89], v[68:71], off offset:16
